# LDS bank conflicts: V transpose staging writes rotated per lane so the eight lanes of a token hit distinct banks (GLA, mLSTM); conv lane mapping changed so transposed b64 writes spread over banks (SSD
# speedup vs baseline: 1.0022x; 1.0022x over previous
.LBB0_404:
	s_or_b64 exec, exec, s[56:57]
	s_and_b64 s[30:31], s[40:41], exec
	s_mov_b32 s9, 0xab34000
	s_cselect_b32 s9, s9, 0xed34000
	v_readlane_b32 s30, v254, 53
	s_add_u32 s29, s30, s9
	v_min_i32_e32 v0, 0xbf, v69
	s_movk_i32 s9, 0xffbf
	v_add_u32_e32 v0, 64, v0
	v_cmp_lt_i32_e32 vcc, s9, v69
	v_min_i32_e32 v4, 0xbf, v70
	v_add_u32_e32 v4, 64, v4
	v_cndmask_b32_e32 v0, 0, v0, vcc
	v_cmp_lt_i32_e32 vcc, s9, v70
	v_cndmask_b32_e64 v78, 64, -1, s[44:45]
	v_sub_u32_e32 v1, 0xff, v0
	v_cndmask_b32_e32 v4, 0, v4, vcc
	v_sub_u32_e32 v5, 0xff, v4
	v_add_u32_e32 v8, 64, v78
	v_sub_u32_e32 v9, 0xbf, v78
	v_add_u32_e32 v14, 64, v71
	v_sub_u32_e32 v15, 0xbf, v71
	v_cndmask_b32_e64 v0, v1, v0, s[40:41]
	v_cndmask_b32_e64 v4, v5, v4, s[40:41]
	v_cndmask_b32_e64 v8, v9, v8, s[40:41]
	v_cndmask_b32_e64 v14, v15, v14, s[40:41]
	v_or_b32_e32 v20, 64, v62
	v_xor_b32_e32 v21, 0xbf, v62
	v_add_u32_e32 v0, s16, v0
	v_mov_b64_e32 v[12:13], s[12:13]
	v_add_u32_e32 v4, s16, v4
	v_add_u32_e32 v8, s16, v8
	v_add_u32_e32 v14, s16, v14
	v_cndmask_b32_e64 v20, v21, v20, s[40:41]
	v_mad_i64_i32 v[0:1], s[34:35], v0, s20, v[12:13]
	v_mad_i64_i32 v[4:5], s[34:35], v4, s20, v[12:13]
	v_mul_lo_u32 v8, v8, s20
	v_mov_b32_e32 v9, v169
	v_mad_i64_i32 v[12:13], s[34:35], v14, s20, v[12:13]
	v_or_b32_e32 v20, s16, v20
	v_mov_b32_e32 v19, v169
	v_lshl_add_u64 v[8:9], s[12:13], 0, v[8:9]
	v_lshl_add_u64 v[12:13], v[12:13], 0, s[84:85]
	v_mul_lo_u32 v20, v20, s21
	v_mov_b32_e32 v21, v169
	v_lshl_add_u64 v[0:1], v[0:1], 0, v[18:19]
	v_lshl_add_u64 v[4:5], v[4:5], 0, v[18:19]
	v_lshl_add_u64 v[8:9], v[8:9], 0, v[18:19]
	v_lshl_add_u64 v[12:13], v[12:13], 0, v[168:169]
	v_lshl_add_u64 v[20:21], s[14:15], 0, v[20:21]
	s_mov_b32 s9, s85
	v_lshl_add_u64 v[0:1], v[0:1], 0, s[84:85]
	v_lshl_add_u64 v[4:5], v[4:5], 0, s[84:85]
	v_lshl_add_u64 v[8:9], v[8:9], 0, s[84:85]
	v_add_co_u32_e32 v12, vcc, s38, v12
	v_lshl_add_u64 v[20:21], v[20:21], 0, s[8:9]
	s_mov_b32 s77, s85
	v_ashrrev_i32_e32 v31, 6, v16
	v_lshl_add_u64 v[0:1], v[0:1], 0, v[168:169]
	v_lshl_add_u64 v[4:5], v[4:5], 0, v[168:169]
	v_lshl_add_u64 v[8:9], v[8:9], 0, v[168:169]
	v_addc_co_u32_e32 v13, vcc, 0, v13, vcc
	v_lshl_add_u64 v[20:21], v[20:21], 0, s[76:77]
	s_movk_i32 s9, 0x880
	v_lshlrev_b32_e32 v80, 1, v62
	global_load_dwordx4 v[0:3], v[0:1], off offset:3664
	v_mul_lo_u32 v79, v31, s9
	global_load_dwordx4 v[4:7], v[4:5], off offset:3664
	s_movk_i32 s9, 0x480
	global_load_dwordx4 v[8:11], v[8:9], off offset:3664
	s_movk_i32 s34, 0x90
	global_load_dwordx4 v[12:15], v[12:13], off offset:592
	s_nop 0
	global_load_dword v82, v[20:21], off offset:256
	global_load_dword v83, v[20:21], off offset:272
	v_add_u32_e32 v20, 0, v80
	v_add_u32_e32 v22, v20, v79
	s_waitcnt lgkmcnt(0)
	s_barrier
	ds_read_u16 v21, v22 offset:59904
	ds_read_u16 v23, v22 offset:60176
	ds_read_u16 v24, v22 offset:60448
	v_mov_b32_e32 v51, v50
	v_mov_b32_e32 v49, v48
	s_waitcnt lgkmcnt(2)
	v_lshlrev_b32_e32 v21, 16, v21
	s_waitcnt lgkmcnt(1)
	v_lshlrev_b32_e32 v23, 16, v23
	v_mul_f32_e32 v25, v64, v23
	s_waitcnt lgkmcnt(0)
	v_lshlrev_b32_e32 v24, 16, v24
	v_fmac_f32_e32 v25, v63, v21
	v_fmac_f32_e32 v25, v65, v24
	v_add_f32_e32 v21, v66, v25
	v_mul_f32_e32 v25, 0xbfb8aa3b, v21
	v_exp_f32_e32 v25, v25
	v_mul_f32_e32 v26, v64, v24
	v_fmac_f32_e32 v26, v63, v23
	v_mov_b32_e32 v53, v52
	v_add_f32_e32 v25, 1.0, v25
	v_rcp_f32_e32 v25, v25
	v_mov_b32_e32 v55, v54
	v_readlane_b32 s31, v254, 54
	s_addc_u32 s30, s31, 0
	v_mul_f32_e32 v21, v21, v25
	v_mul_lo_u32 v25, v31, s9
	v_cvt_pk_bf16_f32 v21, v21, s0
	v_add_u32_e32 v81, v20, v25
	ds_write_b16 v81, v21
	v_lshl_or_b32 v21, v31, 3, 1
	v_mul_lo_u32 v84, v21, s36
	v_add_u32_e32 v32, v20, v84
	ds_read_u16 v25, v32 offset:60448
	v_mul_lo_u32 v21, v21, s34
	v_add_u32_e32 v85, v20, v21
	ds_read_u16 v20, v32 offset:60720
	s_add_i32 s9, 0, 0x13720
	s_waitcnt lgkmcnt(1)
	v_lshlrev_b32_e32 v25, 16, v25
	v_fmac_f32_e32 v26, v65, v25
	v_add_f32_e32 v23, v66, v26
	v_mul_f32_e32 v26, 0xbfb8aa3b, v23
	v_exp_f32_e32 v26, v26
	v_mul_f32_e32 v21, v64, v25
	s_waitcnt lgkmcnt(0)
	v_lshlrev_b32_e32 v20, 16, v20
	v_fmac_f32_e32 v21, v63, v24
	v_add_f32_e32 v26, 1.0, v26
	v_rcp_f32_e32 v26, v26
	v_fmac_f32_e32 v21, v65, v20
	v_add_f32_e32 v21, v66, v21
	v_lshl_add_u32 v92, v31, 5, s9
	v_mul_f32_e32 v23, v23, v26
	v_cvt_pk_bf16_f32 v23, v23, s0
	ds_write_b16 v85, v23
	v_mul_f32_e32 v23, 0xbfb8aa3b, v21
	v_exp_f32_e32 v23, v23
	s_add_i32 s31, 0, 0x13020
	v_and_b32_e32 v28, 1, v31
	v_lshrrev_b32_e32 v30, 4, v62
	v_add_f32_e32 v23, 1.0, v23
	v_rcp_f32_e32 v23, v23
	v_lshlrev_b32_e32 v29, 5, v28
	v_and_b32_e32 v95, 48, v16
	v_cmp_gt_u32_e32 vcc, 16, v16
	v_mul_f32_e32 v21, v21, v23
	v_cvt_pk_bf16_f32 v21, v21, s0
	ds_write_b16 v85, v21 offset:144
	ds_read_u16 v21, v32 offset:60992
	v_mul_f32_e32 v23, v64, v20
	v_fmac_f32_e32 v23, v63, v25
	v_mov_b32_e32 v16, 0x4510
	s_lshl_b32 s28, s28, 13
	s_waitcnt lgkmcnt(0)
	v_lshlrev_b32_e32 v21, 16, v21
	v_fmac_f32_e32 v23, v65, v21
	v_add_f32_e32 v23, v66, v23
	v_mul_f32_e32 v24, 0xbfb8aa3b, v23
	v_exp_f32_e32 v24, v24
	v_cndmask_b32_e64 v106, v16, 0, vcc
	v_lshlrev_b32_e32 v16, 3, v30
	v_mul_u32_u24_e32 v103, 0x90, v17
	v_add_f32_e32 v24, 1.0, v24
	v_rcp_f32_e32 v24, v24
	v_mad_u32_u24 v104, v17, s34, 0
	v_cmp_eq_u32_e64 s[50:51], 0, v17
	v_cmp_lt_u32_e64 s[52:53], 1, v17
	v_mul_f32_e32 v23, v23, v24
	v_cvt_pk_bf16_f32 v23, v23, s0
	ds_write_b16 v85, v23 offset:288
	ds_read_u16 v23, v32 offset:61264
	v_mul_f32_e32 v24, v64, v21
	v_fmac_f32_e32 v24, v63, v20
	v_cmp_lt_u32_e64 s[54:55], 3, v17
	v_cmp_lt_u32_e64 s[56:57], 7, v17
	s_waitcnt lgkmcnt(0)
	v_lshlrev_b32_e32 v23, 16, v23
	v_fmac_f32_e32 v24, v65, v23
	v_add_f32_e32 v20, v66, v24
	v_mul_f32_e32 v24, 0xbfb8aa3b, v20
	v_exp_f32_e32 v24, v24
	v_lshl_add_u64 v[18:19], s[12:13], 0, v[18:19]
	v_lshl_add_u64 v[18:19], v[18:19], 0, s[84:85]
	v_lshl_add_u64 v[56:57], v[18:19], 0, v[168:169]
	v_add_f32_e32 v24, 1.0, v24
	v_rcp_f32_e32 v24, v24
	v_lshlrev_b32_e32 v18, 6, v28
	v_mov_b32_e32 v19, v169
	s_mov_b32 s17, 0
	v_mul_f32_e32 v20, v20, v24
	v_cvt_pk_bf16_f32 v20, v20, s0
	ds_write_b16 v85, v20 offset:432
	ds_read_u16 v20, v32 offset:61536
	v_mul_f32_e32 v24, v64, v23
	v_fmac_f32_e32 v24, v63, v21
	v_cmp_eq_u32_e64 s[48:49], 0, v28
	v_add_u32_e32 v86, 0x110, v84
	s_waitcnt lgkmcnt(0)
	v_lshlrev_b32_e32 v20, 16, v20
	v_fmac_f32_e32 v24, v65, v20
	v_add_f32_e32 v21, v66, v24
	v_mul_f32_e32 v24, 0xbfb8aa3b, v21
	v_exp_f32_e32 v24, v24
	v_add_u32_e32 v87, 0x220, v84
	v_add_u32_e32 v88, 0x330, v84
	v_add_u32_e32 v89, 0x440, v84
	v_add_f32_e32 v24, 1.0, v24
	v_rcp_f32_e32 v24, v24
	v_add_u32_e32 v90, 0x550, v84
	v_add_u32_e32 v91, 0x660, v84
	v_add_u32_e32 v97, 0, v95
	v_mul_f32_e32 v21, v21, v24
	v_cvt_pk_bf16_f32 v21, v21, s0
	ds_write_b16 v85, v21 offset:576
	ds_read_u16 v21, v32 offset:61808
	v_mul_f32_e32 v24, v64, v20
	v_fmac_f32_e32 v24, v63, v23
	v_cndmask_b32_e64 v105, 64, -1, vcc
	v_cmp_lt_u32_e64 s[58:59], 31, v62
	s_waitcnt lgkmcnt(0)
	v_lshlrev_b32_e32 v21, 16, v21
	v_fmac_f32_e32 v24, v65, v21
	v_add_f32_e32 v23, v66, v24
	v_mul_f32_e32 v24, 0xbfb8aa3b, v23
	v_exp_f32_e32 v24, v24
	v_mul_f32_e32 v21, v64, v21
	v_fmac_f32_e32 v21, v63, v20
	v_mov_b32_e32 v115, 0
	v_add_f32_e32 v24, 1.0, v24
	v_rcp_f32_e32 v24, v24
	s_nop 0
	v_mul_f32_e32 v23, v23, v24
	v_cvt_pk_bf16_f32 v23, v23, s0
	ds_write_b16 v85, v23 offset:720
	ds_read_u16 v23, v32 offset:62080
	s_waitcnt lgkmcnt(0)
	v_lshlrev_b32_e32 v23, 16, v23
	v_fmac_f32_e32 v21, v65, v23
	v_add_f32_e32 v20, v66, v21
	v_mul_f32_e32 v21, 0xbfb8aa3b, v20
	v_exp_f32_e32 v21, v21
	s_nop 0
	v_add_f32_e32 v21, 1.0, v21
	v_rcp_f32_e32 v21, v21
	s_nop 0
	v_mul_f32_e32 v20, v20, v21
	v_cvt_pk_bf16_f32 v20, v20, s0
	ds_write_b16 v85, v20 offset:864
	ds_read_u16 v20, v32 offset:61392
	ds_read_u16 v21, v32 offset:61664
	ds_read_u16 v23, v32 offset:61936
	ds_read_u16 v24, v32 offset:62208
	ds_read_u16 v26, v32 offset:60848
	ds_read_u16 v27, v32 offset:61120
	ds_read_u16 v33, v22 offset:60576
	ds_read_u16 v32, v32 offset:60576
	s_waitcnt lgkmcnt(7)
	v_lshlrev_b32_e32 v20, 16, v20
	s_waitcnt lgkmcnt(6)
	v_lshlrev_b32_e32 v21, 16, v21
	s_waitcnt lgkmcnt(3)
	v_lshlrev_b32_e32 v26, 16, v26
	s_waitcnt lgkmcnt(1)
	v_lshlrev_b32_e32 v36, 16, v33
	s_waitcnt lgkmcnt(0)
	v_lshlrev_b32_e32 v37, 16, v32
	ds_read_u16 v32, v22 offset:60032
	ds_read_u16 v22, v22 offset:60304
	v_lshlrev_b32_e32 v27, 16, v27
	v_lshlrev_b32_e32 v25, 16, v23
	v_lshlrev_b32_e32 v23, 16, v24
	s_waitcnt lgkmcnt(1)
	v_lshlrev_b32_e32 v38, 16, v32
	s_waitcnt lgkmcnt(0)
	v_lshlrev_b32_e32 v39, 16, v22
	v_pk_mov_b32 v[40:41], v[38:39], v[36:37] op_sel:[1,0]
	ds_read_b128 v[32:35], v92
	v_pk_mul_f32 v[40:41], v[50:51], v[40:41] op_sel_hi:[0,1]
	v_pk_fma_f32 v[38:39], v[48:49], v[38:39], v[40:41] op_sel_hi:[0,1,1]
	v_pk_fma_f32 v[38:39], v[52:53], v[36:37], v[38:39] op_sel_hi:[0,1,1]
	v_pk_add_f32 v[38:39], v[54:55], v[38:39] op_sel_hi:[0,1]
	v_mul_f32_e32 v22, 0xbfb8aa3b, v38
	v_exp_f32_e32 v22, v22
	v_mov_b32_e32 v24, v21
	v_add_f32_e32 v22, 1.0, v22
	v_rcp_f32_e32 v40, v22
	v_mul_f32_e32 v22, 0xbfb8aa3b, v39
	v_exp_f32_e32 v22, v22
	s_nop 0
	v_add_f32_e32 v22, 1.0, v22
	v_rcp_f32_e32 v41, v22
	s_nop 0
	v_pk_mul_f32 v[38:39], v[38:39], v[40:41]
	s_nop 0
	v_pk_mul_f32 v[38:39], v[38:39], s[92:93] op_sel_hi:[1,0]
	v_pk_mov_b32 v[40:41], v[26:27], v[20:21] op_sel:[1,0]
	v_cvt_pk_bf16_f32 v22, v38, s0
	ds_write_b16 v81, v22 offset:9216
	v_cvt_pk_bf16_f32 v22, v39, s0
	s_waitcnt lgkmcnt(1)
	v_pk_mul_f32 v[38:39], v[32:33], v[38:39]
	v_pk_mov_b32 v[32:33], v[36:37], v[26:27] op_sel:[1,0]
	ds_write_b16 v85, v22 offset:9216
	v_pk_mul_f32 v[32:33], v[50:51], v[32:33] op_sel_hi:[0,1]
	v_pk_fma_f32 v[32:33], v[48:49], v[36:37], v[32:33] op_sel_hi:[0,1,1]
	v_pk_fma_f32 v[32:33], v[52:53], v[26:27], v[32:33] op_sel_hi:[0,1,1]
	v_pk_add_f32 v[32:33], v[54:55], v[32:33] op_sel_hi:[0,1]
	v_mul_f32_e32 v22, 0xbfb8aa3b, v32
	v_exp_f32_e32 v22, v22
	v_pk_mul_f32 v[40:41], v[50:51], v[40:41] op_sel_hi:[0,1]
	v_pk_fma_f32 v[26:27], v[48:49], v[26:27], v[40:41] op_sel_hi:[0,1,1]
	v_pk_fma_f32 v[26:27], v[52:53], v[20:21], v[26:27] op_sel_hi:[0,1,1]
	v_add_f32_e32 v22, 1.0, v22
	v_rcp_f32_e32 v36, v22
	v_mul_f32_e32 v22, 0xbfb8aa3b, v33
	v_exp_f32_e32 v22, v22
	v_pk_add_f32 v[26:27], v[54:55], v[26:27] op_sel_hi:[0,1]
	v_add_f32_e32 v22, 1.0, v22
	v_rcp_f32_e32 v37, v22
	s_nop 0
	v_pk_mul_f32 v[32:33], v[32:33], v[36:37]
	s_nop 0
	v_pk_mul_f32 v[32:33], v[32:33], s[92:93] op_sel_hi:[1,0]
	s_nop 0
	v_cvt_pk_bf16_f32 v22, v32, s0
	ds_write_b16 v85, v22 offset:9360
	v_cvt_pk_bf16_f32 v22, v33, s0
	ds_write_b16 v85, v22 offset:9504
	v_mul_f32_e32 v22, 0xbfb8aa3b, v26
	v_exp_f32_e32 v22, v22
	v_pk_mul_f32 v[36:37], v[34:35], v[32:33]
	ds_read_b128 v[32:35], v92 offset:16
	v_add_f32_e32 v22, 1.0, v22
	v_rcp_f32_e32 v40, v22
	v_mul_f32_e32 v22, 0xbfb8aa3b, v27
	v_exp_f32_e32 v22, v22
	s_nop 0
	v_add_f32_e32 v22, 1.0, v22
	v_rcp_f32_e32 v41, v22
	s_nop 0
	v_pk_mul_f32 v[26:27], v[26:27], v[40:41]
	s_nop 0
	v_pk_mul_f32 v[26:27], v[26:27], s[92:93] op_sel_hi:[1,0]
	s_nop 0
	v_cvt_pk_bf16_f32 v22, v26, s0
	ds_write_b16 v85, v22 offset:9648
	v_cvt_pk_bf16_f32 v22, v27, s0
	ds_write_b16 v85, v22 offset:9792
	v_mov_b32_e32 v22, v25
	v_pk_mul_f32 v[24:25], v[50:51], v[24:25] op_sel_hi:[0,1]
	v_pk_fma_f32 v[20:21], v[48:49], v[20:21], v[24:25] op_sel_hi:[0,1,1]
	v_pk_fma_f32 v[20:21], v[52:53], v[22:23], v[20:21] op_sel_hi:[0,1,1]
	v_pk_add_f32 v[20:21], v[54:55], v[20:21] op_sel_hi:[0,1]
	v_mul_f32_e32 v22, 0xbfb8aa3b, v20
	v_mul_f32_e32 v23, 0xbfb8aa3b, v21
	v_exp_f32_e32 v22, v22
	v_exp_f32_e32 v23, v23
	s_waitcnt lgkmcnt(2)
	v_pk_mul_f32 v[26:27], v[32:33], v[26:27]
	v_lshlrev_b32_e32 v32, 8, v30
	v_add_f32_e32 v22, 1.0, v22
	v_add_f32_e32 v23, 1.0, v23
	v_rcp_f32_e32 v22, v22
	v_rcp_f32_e32 v23, v23
	v_add_u32_e32 v33, v104, v16
	v_pk_mul_f32 v[20:21], v[20:21], v[22:23]
	s_nop 0
	v_pk_mul_f32 v[20:21], v[20:21], s[92:93] op_sel_hi:[1,0]
	s_nop 0
	v_cvt_pk_bf16_f32 v22, v20, s0
	v_pk_mul_f32 v[24:25], v[34:35], v[20:21]
	ds_write_b16 v85, v22 offset:9936
	v_cvt_pk_bf16_f32 v22, v21, s0
	v_cvt_pk_bf16_f32 v23, v24, v25
	v_mul_u32_u24_e32 v24, 0x90, v62
	v_lshlrev_b32_e32 v25, 4, v31
	ds_write_b16 v85, v22 offset:10080
	v_cvt_pk_bf16_f32 v20, v38, v39
	v_cvt_pk_bf16_f32 v21, v36, v37
	v_cvt_pk_bf16_f32 v22, v26, v27
	v_add3_u32 v93, 0, v24, v25
	ds_write_b128 v93, v[20:23] offset:18432
	v_and_b32_e32 v20, -16, v71
	v_or_b32_e32 v94, v20, v17
	v_lshlrev_b32_e32 v22, 2, v62
	v_mul_lo_u32 v21, v94, s34
	v_add_u32_e32 v98, s31, v22
	s_add_i32 s31, 0, 0x13120
	v_add_u32_e32 v31, 0, v21
	v_lshlrev_b32_e32 v21, 2, v30
	v_add_u32_e32 v99, s31, v22
	s_add_i32 s31, 0, 0x13220
	v_add_u32_e32 v101, s9, v22
	v_readlane_b32 s9, v253, 45
	v_lshlrev_b32_e32 v30, 1, v20
	v_or_b32_e32 v20, v29, v17
	v_or_b32_e32 v109, v29, v21
	s_add_u32 s8, s14, s8
	v_lshl_add_u32 v102, v94, 2, s9
	v_mul_u32_u24_e32 v108, 0x90, v20
	v_or_b32_e32 v20, 3, v109
	s_addc_u32 s9, s15, 0
	v_cmp_gt_i32_e64 s[64:65], v20, v94
	v_or_b32_e32 v20, 16, v29
	s_add_u32 s8, s8, s76
	v_or_b32_e32 v17, v20, v17
	s_addc_u32 s9, s9, 0
	v_mul_u32_u24_e32 v110, 0x90, v17
	v_or_b32_e32 v17, v20, v21
	s_add_u32 s34, s29, s84
	v_cmp_gt_i32_e64 s[68:69], v17, v94
	v_cmp_lt_i32_e64 s[70:71], v17, v94
	v_or_b32_e32 v20, 3, v17
	v_or_b32_e32 v21, 2, v17
	v_lshlrev_b32_e32 v29, 1, v17
	s_addc_u32 s35, s30, 0
	v_mov_b32_e32 v17, v169
	v_add_u32_e32 v100, s31, v22
	v_add3_u32 v107, 0, v16, v30
	v_or_b32_e32 v22, 2, v109
	v_lshlrev_b32_e32 v34, 1, v109
	v_lshl_add_u64 v[16:17], s[34:35], 0, v[16:17]
	v_add_u32_e32 v96, v31, v95
	v_cmp_gt_i32_e64 s[60:61], v109, v94
	v_cmp_lt_i32_e64 s[62:63], v109, v94
	v_cmp_gt_i32_e64 s[66:67], v22, v94
	v_cmp_gt_i32_e64 s[72:73], v20, v94
	v_cmp_gt_i32_e64 s[74:75], v21, v94
	v_lshl_add_u64 v[58:59], v[16:17], 0, v[18:19]
	v_mov_b32_e32 v24, 0
	v_mov_b32_e32 v25, 0
	v_mov_b32_e32 v26, 0
	v_mov_b32_e32 v27, 0
	v_mov_b32_e32 v16, 0
	v_mov_b32_e32 v17, 0
	v_mov_b32_e32 v18, 0
	v_mov_b32_e32 v19, 0
	v_mov_b32_e32 v20, 0
	v_mov_b32_e32 v21, 0
	v_mov_b32_e32 v22, 0
	v_mov_b32_e32 v23, 0
	v_add_u32_e32 v111, v31, v34
	v_add_u32_e32 v112, v31, v29
	v_add_u32_e32 v113, v102, v32
	v_add_u32_e32 v114, v33, v30
	s_mov_b32 s29, 0
	s_waitcnt lgkmcnt(0)
	s_barrier
	v_lshrrev_b32_e32 v196, 6, v171
	v_lshlrev_b32_e32 v196, 1, v196
	v_bfe_u32 v197, v171, 3, 1
	v_add_u32_e32 v196, v196, v197
	v_lshlrev_b32_e32 v196, 2, v196
	v_bfe_u32 v197, v171, 4, 2
	v_lshlrev_b32_e32 v197, 3, v197
	v_and_b32_e32 v202, 7, v171
	v_add_u32_e32 v197, v197, v202
	v_mul_u32_u24_e32 v198, 0x110, v196
	v_lshl_add_u32 v198, v197, 2, v198
	v_add_u32_e32 v198, 0xea00, v198
	v_mul_u32_u24_e32 v199, 0x90, v196
	v_lshl_add_u32 v199, v197, 2, v199
	v_mul_u32_u24_e32 v200, 0x120, v197
	v_lshl_add_u32 v200, v196, 1, v200
	v_lshlrev_b32_e32 v201, 2, v196
	v_add_u32_e32 v201, 0x13720, v201
	v_lshlrev_b32_e32 v202, 3, v197
	v_add_u32_e32 v203, 4, v202
	ds_bpermute_b32 v172, v202, v63
	ds_bpermute_b32 v173, v203, v63
	ds_bpermute_b32 v174, v202, v64
	ds_bpermute_b32 v175, v203, v64
	ds_bpermute_b32 v176, v202, v65
	ds_bpermute_b32 v177, v203, v65
	ds_bpermute_b32 v178, v202, v66
	ds_bpermute_b32 v179, v203, v66
	ds_bpermute_b32 v180, v202, v48
	ds_bpermute_b32 v181, v203, v48
	ds_bpermute_b32 v182, v202, v50
	ds_bpermute_b32 v183, v203, v50
	ds_bpermute_b32 v184, v202, v52
	ds_bpermute_b32 v185, v203, v52
	ds_bpermute_b32 v186, v202, v54
	ds_bpermute_b32 v187, v203, v54
	s_waitcnt lgkmcnt(0)
	v_and_b32_e32 v240, 7, v171
	v_lshrrev_b32_e32 v239, 3, v171
	v_lshlrev_b32_e32 v239, 1, v239
	v_add_u32_e32 v222, 0, v240
	v_and_b32_e32 v222, 7, v222
	v_lshl_add_u32 v222, v240, 3, v222
	v_mul_u32_u24_e32 v222, 0x90, v222
	v_add_u32_e32 v222, v222, v239
	v_add_u32_e32 v223, 1, v240
	v_and_b32_e32 v223, 7, v223
	v_lshl_add_u32 v223, v240, 3, v223
	v_mul_u32_u24_e32 v223, 0x90, v223
	v_add_u32_e32 v223, v223, v239
	v_add_u32_e32 v224, 2, v240
	v_and_b32_e32 v224, 7, v224
	v_lshl_add_u32 v224, v240, 3, v224
	v_mul_u32_u24_e32 v224, 0x90, v224
	v_add_u32_e32 v224, v224, v239
	v_add_u32_e32 v225, 3, v240
	v_and_b32_e32 v225, 7, v225
	v_lshl_add_u32 v225, v240, 3, v225
	v_mul_u32_u24_e32 v225, 0x90, v225
	v_add_u32_e32 v225, v225, v239
	v_add_u32_e32 v226, 4, v240
	v_and_b32_e32 v226, 7, v226
	v_lshl_add_u32 v226, v240, 3, v226
	v_mul_u32_u24_e32 v226, 0x90, v226
	v_add_u32_e32 v226, v226, v239
	v_add_u32_e32 v227, 5, v240
	v_and_b32_e32 v227, 7, v227
	v_lshl_add_u32 v227, v240, 3, v227
	v_mul_u32_u24_e32 v227, 0x90, v227
	v_add_u32_e32 v227, v227, v239
	v_add_u32_e32 v228, 6, v240
	v_and_b32_e32 v228, 7, v228
	v_lshl_add_u32 v228, v240, 3, v228
	v_mul_u32_u24_e32 v228, 0x90, v228
	v_add_u32_e32 v228, v228, v239
	v_add_u32_e32 v229, 7, v240
	v_and_b32_e32 v229, 7, v229
	v_lshl_add_u32 v229, v240, 3, v229
	v_mul_u32_u24_e32 v229, 0x90, v229
	v_add_u32_e32 v229, v229, v239
	v_and_b32_e32 v230, 1, v171
	v_lshlrev_b32_e32 v230, 4, v230
	s_branch .LBB0_406

.LBB0_411:
	s_or_b64 exec, exec, s[78:79]
	s_mul_i32 s38, s36, 0x2d00
	s_add_i32 s37, s37, s38
	v_add3_u32 v42, s37, v77, v76
	s_waitcnt vmcnt(2)
	v_alignbit_b32 v231, v13, v12, v230
	v_alignbit_b32 v232, v14, v13, v230
	v_alignbit_b32 v233, v15, v14, v230
	v_alignbit_b32 v234, v12, v15, v230
	v_and_b32_e32 v240, 2, v171
	v_cmp_ne_u32_e64 s[78:79], 0, v240
	v_and_b32_e32 v240, 4, v171
	s_nop 0
	v_cndmask_b32_e64 v235, v231, v232, s[78:79]
	v_cndmask_b32_e64 v236, v232, v233, s[78:79]
	v_cndmask_b32_e64 v237, v233, v234, s[78:79]
	v_cndmask_b32_e64 v238, v234, v231, s[78:79]
	v_cmp_ne_u32_e64 s[78:79], 0, v240
	s_nop 1
	v_cndmask_b32_e64 v231, v235, v237, s[78:79]
	v_cndmask_b32_e64 v232, v236, v238, s[78:79]
	v_cndmask_b32_e64 v233, v237, v235, s[78:79]
	v_cndmask_b32_e64 v234, v238, v236, s[78:79]
	v_add_u32_e32 v239, s37, v222
	ds_write_b16 v239, v231 offset:36864
	v_add_u32_e32 v239, s37, v223
	ds_write_b16_d16_hi v239, v231 offset:36864
	v_add_u32_e32 v239, s37, v224
	ds_write_b16 v239, v232 offset:36864
	v_add_u32_e32 v239, s37, v225
	ds_write_b16_d16_hi v239, v232 offset:36864
	v_add_u32_e32 v239, s37, v226
	ds_write_b16 v239, v233 offset:36864
	v_add_u32_e32 v239, s37, v227
	ds_write_b16_d16_hi v239, v233 offset:36864
	v_add_u32_e32 v239, s37, v228
	ds_write_b16 v239, v234 offset:36864
	v_add_u32_e32 v239, s37, v229
	ds_write_b16_d16_hi v239, v234 offset:36864
	s_and_saveexec_b64 s[76:77], s[46:47]
	s_cbranch_execz .LBB0_413
	s_waitcnt vmcnt(0)
	v_add_f32_e32 v42, v68, v83
	v_min_f32_e32 v43, 0, v42
	v_mul_f32_e64 v42, |v42|, s19
	v_exp_f32_e32 v42, v42
	s_waitcnt lgkmcnt(10)
	v_add_f32_e32 v40, v40, v41
	v_add_f32_e32 v41, v67, v82
	v_add_f32_e32 v42, 1.0, v42
	v_log_f32_e32 v42, v42
	s_mulk_i32 s36, 0x7c00
	s_nop 0
	v_fmac_f32_e32 v43, 0xbf317218, v42
	s_nop 1
	v_add_f32_dpp v43, v43, v43 row_shr:1 row_mask:0xf bank_mask:0xf
	s_nop 1
	v_add_f32_dpp v43, v43, v43 row_shr:2 row_mask:0xf bank_mask:0xf
	s_nop 1
	v_add_f32_dpp v43, v43, v43 row_shr:4 row_mask:0xf bank_mask:0xf
	s_nop 1
	v_add_f32_dpp v43, v43, v43 row_shr:8 row_mask:0xf bank_mask:0xf
	s_nop 1
	v_add_f32_dpp v43, v43, v43 row_bcast:15 row_mask:0xa bank_mask:0xf
	s_nop 1
	v_add_f32_dpp v43, v43, v43 row_bcast:31 row_mask:0xc bank_mask:0xf
	s_nop 0
	v_sub_f32_e32 v41, v41, v43
	v_mov_b32_e32 v42, v41
	s_nop 1
	v_max_f32_dpp v42, v42, v42 row_shr:1 row_mask:0xf bank_mask:0xf
	s_nop 1
	v_max_f32_dpp v42, v42, v42 row_shr:2 row_mask:0xf bank_mask:0xf
	s_nop 1
	v_max_f32_dpp v42, v42, v42 row_shr:4 row_mask:0xf bank_mask:0xf
	s_nop 1
	v_max_f32_dpp v42, v42, v42 row_shr:8 row_mask:0xf bank_mask:0xf
	s_nop 1
	v_max_f32_dpp v42, v42, v42 row_bcast:15 row_mask:0xa bank_mask:0xf
	s_nop 1
	v_max_f32_dpp v42, v42, v42 row_bcast:31 row_mask:0xc bank_mask:0xf
	s_nop 0
	v_max_f32_e32 v40, v42, v40
	v_add_u32_e32 v44, s36, v98
	ds_write_b32 v44, v43
	v_add_u32_e32 v44, s36, v99
	ds_write_b32 v44, v41
	v_add_u32_e32 v44, s36, v100
	v_readlane_b32 s37, v40, 63
	ds_write_b32 v44, v40
	s_nop 0
	v_subrev_f32_e32 v40, s37, v41
	v_mul_f32_e32 v40, 0x3fb8aa3b, v40
	v_exp_f32_e32 v40, v40
	v_add_u32_e32 v41, s36, v101
	ds_write_b32 v41, v40

.LBB0_441:
	s_or_b64 exec, exec, s[52:53]
	v_cndmask_b32_e64 v81, 64, -1, s[46:47]
	v_add_u32_e32 v13, 64, v81
	v_sub_u32_e32 v14, 0xbf, v81
	v_cndmask_b32_e64 v13, v14, v13, s[40:41]
	v_add_u32_e32 v13, s28, v13
	v_mul_lo_u32 v14, v13, s20
	v_mov_b32_e32 v15, v169
	v_lshl_add_u64 v[14:15], s[12:13], 0, v[14:15]
	v_mov_b32_e32 v13, v169
	v_lshl_add_u64 v[12:13], v[12:13], 1, v[14:15]
	v_or_b32_e32 v14, 64, v62
	v_xor_b32_e32 v15, 0xbf, v62
	v_cndmask_b32_e64 v14, v15, v14, s[40:41]
	v_or_b32_e32 v14, s28, v14
	s_and_b64 s[16:17], s[40:41], exec
	s_mov_b32 s9, 0xab34000
	v_mul_lo_u32 v14, v14, s21
	v_mov_b32_e32 v15, v169
	s_cselect_b32 s9, s9, 0xed34000
	v_readlane_b32 s16, v254, 53
	v_lshl_add_u64 v[14:15], s[14:15], 0, v[14:15]
	s_add_u32 s16, s16, s9
	v_mov_b32_e32 v57, v169
	v_lshl_add_u64 v[14:15], v[14:15], 0, s[84:85]
	s_mov_b32 s9, s85
	v_ashrrev_i32_e32 v37, 6, v17
	v_lshl_add_u64 v[12:13], v[12:13], 0, v[56:57]
	v_lshl_add_u64 v[18:19], v[14:15], 0, s[8:9]
	global_load_dwordx4 v[12:15], v[12:13], off
	s_nop 0
	global_load_dword v88, v[18:19], off offset:128
	v_lshlrev_b32_e32 v83, 1, v62
	v_lshl_or_b32 v18, v37, 3, 1
	s_movk_i32 s9, 0xc80
	v_add_u32_e32 v16, 0, v83
	v_mul_lo_u32 v86, v18, s29
	s_movk_i32 s35, 0x90
	v_mul_lo_u32 v82, v37, s9
	s_movk_i32 s9, 0x480
	v_add_u32_e32 v61, v16, v86
	v_mul_lo_u32 v97, v18, s35
	v_mul_lo_u32 v95, v37, s9
	v_add_u32_e32 v100, 0x90, v97
	v_add_u32_e32 v102, 0x120, v97
	v_add_u32_e32 v101, 0x4b0, v61
	v_add_u32_e32 v104, 0x1b0, v97
	v_add_u32_e32 v107, 0x240, v97
	v_add_u32_e32 v108, 0x2d0, v97
	v_add_u32_e32 v109, 0x360, v97
	s_waitcnt lgkmcnt(0)
	s_barrier
	v_add_u32_e32 v39, v16, v82
	v_add_u32_e32 v84, v16, v95
	v_add_u32_e32 v87, v16, v97
	v_add_u32_e32 v98, 0x190, v61
	v_add_u32_e32 v89, v16, v100
	v_add_u32_e32 v99, 0x320, v61
	v_add_u32_e32 v90, v16, v102
	v_add_u32_e32 v94, v16, v104
	v_add_u32_e32 v103, 0x640, v61
	v_add_u32_e32 v114, v16, v107
	v_add_u32_e32 v105, 0x7d0, v61
	v_add_u32_e32 v91, v16, v108
	v_add_u32_e32 v106, 0x960, v61
	v_add_u32_e32 v96, v16, v109
	ds_read_u16 v16, v101 offset:65440
	ds_read_u16 v18, v103 offset:65440
	ds_read_u16 v92, v105 offset:65440
	ds_read_u16 v19, v106 offset:65440
	ds_read_u16 v112, v99 offset:65440
	s_waitcnt lgkmcnt(4)
	v_lshlrev_b32_e32 v54, 16, v16
	ds_read_u16 v115, v98 offset:65440
	ds_read_u16 v16, v61 offset:65440
	ds_read_u16 v20, v39 offset:65440
	ds_read_u16 v41, v39 offset:64640
	s_waitcnt vmcnt(5)
	ds_read_u16 v21, v39 offset:65040
	v_mov_b32_e32 v45, v44
	s_waitcnt lgkmcnt(3)
	v_lshlrev_b32_e32 v51, 16, v16
	s_waitcnt lgkmcnt(2)
	v_lshlrev_b32_e32 v50, 16, v20
	s_waitcnt lgkmcnt(1)
	v_lshlrev_b32_e32 v48, 16, v41
	s_waitcnt lgkmcnt(0)
	v_lshlrev_b32_e32 v49, 16, v21
	v_mov_b32_e32 v16, v43
	v_pk_mov_b32 v[52:53], v[48:49], v[50:51] op_sel:[1,0]
	v_mov_b32_e32 v41, v40
	v_pk_mul_f32 v[52:53], v[16:17], v[52:53] op_sel_hi:[0,1]
	v_pk_fma_f32 v[48:49], v[40:41], v[48:49], v[52:53] op_sel_hi:[0,1,1]
	v_pk_fma_f32 v[48:49], v[42:43], v[50:51], v[48:49] op_sel_hi:[0,1,1]
	v_pk_add_f32 v[48:49], v[44:45], v[48:49] op_sel_hi:[0,1]
	v_mul_f32_e32 v52, 0xbfb8aa3b, v48
	v_mul_f32_e32 v53, 0xbfb8aa3b, v49
	v_exp_f32_e32 v52, v52
	v_exp_f32_e32 v53, v53
	v_lshlrev_b32_e32 v113, 16, v112
	v_lshlrev_b32_e32 v112, 16, v115
	v_add_f32_e32 v52, 1.0, v52
	v_add_f32_e32 v53, 1.0, v53
	v_rcp_f32_e32 v52, v52
	v_rcp_f32_e32 v53, v53
	v_lshlrev_b32_e32 v55, 16, v18
	v_lshlrev_b32_e32 v111, 16, v92
	v_mov_b32_e32 v110, v55
	v_pk_mul_f32 v[48:49], v[48:49], v[52:53]
	v_pk_mov_b32 v[52:53], v[50:51], v[112:113] op_sel:[1,0]
	v_cvt_pk_bf16_f32 v92, v48, s0
	v_pk_mul_f32 v[52:53], v[16:17], v[52:53] op_sel_hi:[0,1]
	v_pk_fma_f32 v[50:51], v[40:41], v[50:51], v[52:53] op_sel_hi:[0,1,1]
	v_pk_fma_f32 v[50:51], v[42:43], v[112:113], v[50:51] op_sel_hi:[0,1,1]
	v_pk_add_f32 v[50:51], v[44:45], v[50:51] op_sel_hi:[0,1]
	v_mul_f32_e32 v52, 0xbfb8aa3b, v50
	v_mul_f32_e32 v53, 0xbfb8aa3b, v51
	v_exp_f32_e32 v52, v52
	v_exp_f32_e32 v53, v53
	ds_write_b16 v84, v92 offset:9216
	v_cvt_pk_bf16_f32 v92, v49, s0
	v_add_f32_e32 v52, 1.0, v52
	v_add_f32_e32 v53, 1.0, v53
	v_rcp_f32_e32 v52, v52
	v_rcp_f32_e32 v53, v53
	ds_write_b16 v87, v92 offset:9216
	v_lshlrev_b32_e32 v93, 16, v19
	v_readlane_b32 s17, v254, 54
	v_pk_mul_f32 v[50:51], v[50:51], v[52:53]
	v_pk_mov_b32 v[52:53], v[112:113], v[54:55] op_sel:[1,0]
	v_cvt_pk_bf16_f32 v115, v50, s0
	v_pk_mul_f32 v[52:53], v[16:17], v[52:53] op_sel_hi:[0,1]
	v_pk_fma_f32 v[52:53], v[40:41], v[112:113], v[52:53] op_sel_hi:[0,1,1]
	v_pk_fma_f32 v[52:53], v[42:43], v[54:55], v[52:53] op_sel_hi:[0,1,1]
	v_pk_add_f32 v[52:53], v[44:45], v[52:53] op_sel_hi:[0,1]
	v_mul_f32_e32 v92, 0xbfb8aa3b, v52
	v_exp_f32_e32 v92, v92
	v_mul_f32_e32 v112, 0xbfb8aa3b, v53
	v_exp_f32_e32 v113, v112
	ds_write_b16 v89, v115 offset:9216
	v_add_f32_e32 v92, 1.0, v92
	v_rcp_f32_e32 v112, v92
	v_add_f32_e32 v92, 1.0, v113
	v_rcp_f32_e32 v113, v92
	v_cvt_pk_bf16_f32 v92, v51, s0
	ds_write_b16 v90, v92 offset:9216
	v_mov_b32_e32 v92, v111
	v_pk_mul_f32 v[110:111], v[16:17], v[110:111] op_sel_hi:[0,1]
	v_pk_fma_f32 v[54:55], v[40:41], v[54:55], v[110:111] op_sel_hi:[0,1,1]
	v_pk_fma_f32 v[54:55], v[42:43], v[92:93], v[54:55] op_sel_hi:[0,1,1]
	v_pk_add_f32 v[54:55], v[44:45], v[54:55] op_sel_hi:[0,1]
	v_mul_f32_e32 v16, 0xbfb8aa3b, v54
	v_exp_f32_e32 v16, v16
	v_mul_f32_e32 v92, 0xbfb8aa3b, v55
	v_exp_f32_e32 v93, v92
	v_pk_mul_f32 v[52:53], v[52:53], v[112:113]
	v_add_f32_e32 v16, 1.0, v16
	v_rcp_f32_e32 v92, v16
	v_add_f32_e32 v16, 1.0, v93
	v_rcp_f32_e32 v93, v16
	v_cvt_pk_bf16_f32 v110, v52, s0
	v_cvt_pk_bf16_f32 v16, v53, s0
	ds_write_b16 v94, v110 offset:9216
	v_pk_mul_f32 v[54:55], v[54:55], v[92:93]
	ds_write_b16 v114, v16 offset:9216
	v_cvt_pk_bf16_f32 v16, v54, s0
	v_lshlrev_b32_e32 v35, 5, v37
	s_addc_u32 s17, s17, 0
	s_add_i32 s9, 0, 0x16520
	ds_write_b16 v91, v16 offset:9216
	v_cvt_pk_bf16_f32 v16, v55, s0
	v_add_u32_e32 v46, 0xfc00, v39
	v_add_u32_e32 v85, s9, v35
	ds_write_b16 v96, v16 offset:9216
	ds_read_b128 v[18:21], v85
	ds_read_u16 v16, v39 offset:65168
	ds_read_u16 v46, v46 offset:1056
	ds_read_u16 v92, v39 offset:64768
	v_add_u32_e32 v110, 0x10020, v61
	v_add_u32_e32 v111, 0x101b0, v61
	s_waitcnt lgkmcnt(2)
	v_lshlrev_b32_e32 v16, 16, v16
	s_waitcnt lgkmcnt(1)
	v_lshlrev_b32_e32 v46, 16, v46
	s_waitcnt lgkmcnt(0)
	v_lshlrev_b32_e32 v92, 16, v92
	v_mul_f32_e32 v92, v63, v92
	v_fmac_f32_e32 v92, v64, v16
	v_fmac_f32_e32 v92, v65, v46
	v_add_f32_e32 v92, v66, v92
	v_mul_f32_e32 v93, 0xbfb8aa3b, v92
	v_exp_f32_e32 v93, v93
	v_add_u32_e32 v112, 0x10340, v61
	v_add_u32_e32 v113, 0x104d0, v61
	v_add_u32_e32 v115, 0x10660, v61
	v_add_f32_e32 v93, 1.0, v93
	v_rcp_f32_e32 v93, v93
	ds_read_u16 v110, v110
	ds_read_u16 v111, v111
	ds_read_u16 v112, v112
	ds_read_u16 v113, v113
	ds_read_u16 v115, v115
	v_mul_f32_e32 v16, v63, v16
	s_waitcnt lgkmcnt(4)
	v_lshlrev_b32_e32 v110, 16, v110
	v_fmac_f32_e32 v16, v64, v46
	v_fmac_f32_e32 v16, v65, v110
	v_add_f32_e32 v16, v66, v16
	v_mul_f32_e32 v92, v92, v93
	v_mul_f32_e32 v116, 0xbfb8aa3b, v16
	v_cvt_pk_bf16_f32 v92, v92, s0
	v_mul_f32_e32 v93, v64, v110
	v_exp_f32_e32 v116, v116
	ds_write_b16 v84, v92
	s_waitcnt lgkmcnt(4)
	v_lshlrev_b32_e32 v92, 16, v111
	v_fmac_f32_e32 v93, v63, v46
	v_fmac_f32_e32 v93, v65, v92
	v_add_f32_e32 v46, v66, v93
	s_waitcnt lgkmcnt(3)
	v_lshlrev_b32_e32 v111, 16, v112
	v_mul_f32_e32 v112, v64, v92
	v_mul_f32_e32 v93, 0xbfb8aa3b, v46
	v_fmac_f32_e32 v112, v63, v110
	v_add_f32_e32 v116, 1.0, v116
	v_exp_f32_e32 v93, v93
	v_fmac_f32_e32 v112, v65, v111
	v_rcp_f32_e32 v116, v116
	v_add_f32_e32 v110, v66, v112
	v_mul_f32_e32 v112, 0xbfb8aa3b, v110
	v_exp_f32_e32 v112, v112
	v_add_f32_e32 v93, 1.0, v93
	v_mul_f32_e32 v16, v16, v116
	v_rcp_f32_e32 v93, v93
	v_cvt_pk_bf16_f32 v16, v16, s0
	ds_write_b16 v87, v16
	v_add_f32_e32 v16, 1.0, v112
	v_rcp_f32_e32 v16, v16
	v_mul_f32_e32 v46, v46, v93
	v_cvt_pk_bf16_f32 v46, v46, s0
	ds_write_b16 v89, v46
	s_waitcnt lgkmcnt(4)
	v_lshlrev_b32_e32 v46, 16, v113
	v_mul_f32_e32 v16, v110, v16
	v_mul_f32_e32 v89, v64, v111
	v_mul_f32_e32 v110, v64, v46
	v_fmac_f32_e32 v89, v63, v92
	s_waitcnt lgkmcnt(3)
	v_lshlrev_b32_e32 v93, 16, v115
	v_fmac_f32_e32 v110, v63, v111
	v_fmac_f32_e32 v89, v65, v46
	v_fmac_f32_e32 v110, v65, v93
	v_add_f32_e32 v89, v66, v89
	v_add_f32_e32 v110, v66, v110
	v_mul_f32_e32 v92, 0xbfb8aa3b, v89
	v_mul_f32_e32 v111, 0xbfb8aa3b, v110
	v_exp_f32_e32 v92, v92
	v_exp_f32_e32 v111, v111
	v_cvt_pk_bf16_f32 v16, v16, s0
	ds_write_b16 v90, v16
	v_add_f32_e32 v92, 1.0, v92
	v_add_f32_e32 v16, 1.0, v111
	v_rcp_f32_e32 v92, v92
	v_rcp_f32_e32 v16, v16
	v_pk_mul_f32 v[18:19], v[18:19], v[48:49]
	v_pk_mul_f32 v[20:21], v[20:21], v[50:51]
	v_mul_f32_e32 v89, v89, v92
	v_mul_f32_e32 v16, v110, v16
	v_cvt_pk_bf16_f32 v89, v89, s0
	v_cvt_pk_bf16_f32 v16, v16, s0
	ds_write_b16 v94, v89
	ds_write_b16 v114, v16
	v_add_u32_e32 v16, 0x107f0, v61
	ds_read_u16 v16, v16
	v_or_b32_e32 v114, 16, v35
	v_add_u32_e32 v89, s9, v114
	ds_read_b128 v[110:113], v89
	v_cvt_pk_bf16_f32 v18, v18, v19
	s_waitcnt lgkmcnt(1)
	v_lshlrev_b32_e32 v94, 16, v16
	v_mul_f32_e32 v16, v64, v93
	v_fmac_f32_e32 v16, v63, v46
	v_fmac_f32_e32 v16, v65, v94
	v_add_f32_e32 v92, v66, v16
	v_mul_f32_e32 v16, 0xbfb8aa3b, v92
	v_exp_f32_e32 v46, v16
	v_mul_f32_e32 v94, v64, v94
	v_fmac_f32_e32 v94, v63, v93
	s_waitcnt lgkmcnt(0)
	v_pk_mul_f32 v[50:51], v[112:113], v[54:55]
	v_add_f32_e32 v46, 1.0, v46
	v_rcp_f32_e32 v117, v46
	v_cndmask_b32_e64 v46, 0, v33, s[40:41]
	v_cvt_pk_bf16_f32 v19, v20, v21
	v_cvt_pk_bf16_f32 v21, v50, v51
	v_mul_f32_e32 v33, v92, v117
	v_cvt_pk_bf16_f32 v33, v33, s0
	ds_write_b16 v91, v33
	v_add_u32_e32 v33, 0x10980, v61
	ds_read_u16 v33, v33
	s_movk_i32 s34, 0xff72
	v_and_b32_e32 v115, 32, v35
	v_lshrrev_b32_e32 v116, 4, v62
	v_cmp_gt_u32_e64 s[46:47], 47, v59
	s_waitcnt lgkmcnt(0)
	v_lshlrev_b32_e32 v33, 16, v33
	v_fmac_f32_e32 v94, v65, v33
	v_add_f32_e32 v33, v66, v94
	v_mul_f32_e32 v93, 0xbfb8aa3b, v33
	v_exp_f32_e32 v117, v93
	s_lshl_b32 s30, s30, 13
	v_cmp_eq_u32_e64 s[74:75], 1, v47
	v_mov_b32_e32 v16, 0
	v_add_f32_e32 v48, 1.0, v117
	v_rcp_f32_e32 v117, v48
	v_pk_mul_f32 v[48:49], v[110:111], v[52:53]
	s_mov_b32 s29, 0
	v_cvt_pk_bf16_f32 v20, v48, v49
	v_mul_f32_e32 v33, v33, v117
	v_cvt_pk_bf16_f32 v33, v33, s0
	ds_write_b16 v96, v33
	v_mad_u32_u24 v33, v62, s35, 0
	v_lshl_add_u32 v49, v37, 4, v33
	ds_write_b128 v49, v[18:21] offset:27648
	v_mad_i32_i24 v18, v62, s34, v33
	v_add_u32_e32 v95, v18, v95
	s_add_i32 s34, 0, 0x16420
	v_add_u32_e32 v97, v18, v97
	v_add_u32_e32 v48, v18, v100
	v_add_u32_e32 v52, v18, v102
	v_add_u32_e32 v110, v18, v104
	v_add_u32_e32 v107, v18, v107
	v_add_u32_e32 v108, v18, v108
	v_add_u32_e32 v109, v18, v109
	ds_read_u16 v18, v101 offset:65312
	ds_read_u16 v19, v103 offset:65312
	ds_read_u16 v102, v105 offset:65312
	ds_read_u16 v20, v106 offset:65312
	ds_read_u16 v104, v99 offset:65312
	v_add_u32_e32 v96, s34, v35
	s_waitcnt lgkmcnt(4)
	v_lshlrev_b32_e32 v50, 16, v18
	ds_read_u16 v106, v98 offset:65312
	ds_read_u16 v18, v61 offset:65312
	ds_read_u16 v21, v39 offset:65312
	ds_read_u16 v33, v39 offset:64512
	ds_read_u16 v35, v39 offset:64912
	v_mov_b32_e32 v37, v36
	s_waitcnt lgkmcnt(3)
	v_lshlrev_b32_e32 v55, 16, v18
	s_waitcnt lgkmcnt(2)
	v_lshlrev_b32_e32 v54, 16, v21
	s_waitcnt lgkmcnt(1)
	v_lshlrev_b32_e32 v98, 16, v33
	s_waitcnt lgkmcnt(0)
	v_lshlrev_b32_e32 v99, 16, v35
	v_mov_b32_e32 v35, v34
	v_pk_mov_b32 v[100:101], v[98:99], v[54:55] op_sel:[1,0]
	v_mov_b32_e32 v33, v32
	v_pk_mul_f32 v[100:101], v[34:35], v[100:101] op_sel_hi:[0,1]
	v_pk_fma_f32 v[98:99], v[32:33], v[98:99], v[100:101] op_sel_hi:[0,1,1]
	v_pk_fma_f32 v[98:99], v[36:37], v[54:55], v[98:99] op_sel_hi:[0,1,1]
	v_mov_b32_e32 v39, v38
	v_pk_add_f32 v[98:99], v[38:39], v[98:99] op_sel_hi:[0,1]
	v_mul_f32_e32 v61, 0xbfb8aa3b, v98
	v_exp_f32_e32 v61, v61
	v_mul_f32_e32 v100, 0xbfb8aa3b, v99
	v_exp_f32_e32 v100, v100
	v_lshlrev_b32_e32 v101, 16, v102
	v_add_f32_e32 v61, 1.0, v61
	v_rcp_f32_e32 v102, v61
	v_add_f32_e32 v61, 1.0, v100
	v_rcp_f32_e32 v103, v61
	v_lshlrev_b32_e32 v105, 16, v104
	v_lshlrev_b32_e32 v104, 16, v106
	v_lshlrev_b32_e32 v51, 16, v19
	v_pk_mul_f32 v[98:99], v[98:99], v[102:103]
	v_pk_mov_b32 v[102:103], v[54:55], v[104:105] op_sel:[1,0]
	v_cvt_pk_bf16_f32 v61, v98, s0
	v_pk_mul_f32 v[102:103], v[34:35], v[102:103] op_sel_hi:[0,1]
	v_pk_fma_f32 v[54:55], v[32:33], v[54:55], v[102:103] op_sel_hi:[0,1,1]
	v_pk_fma_f32 v[54:55], v[36:37], v[104:105], v[54:55] op_sel_hi:[0,1,1]
	v_pk_add_f32 v[54:55], v[38:39], v[54:55] op_sel_hi:[0,1]
	v_mul_f32_e32 v102, 0xbfb8aa3b, v54
	v_exp_f32_e32 v102, v102
	v_mul_f32_e32 v103, 0xbfb8aa3b, v55
	v_exp_f32_e32 v103, v103
	ds_write_b16 v95, v61 offset:55296
	v_add_f32_e32 v61, 1.0, v102
	v_lshlrev_b32_e32 v53, 16, v20
	ds_read_b128 v[18:21], v96
	v_rcp_f32_e32 v102, v61
	v_add_f32_e32 v61, 1.0, v103
	v_rcp_f32_e32 v103, v61
	v_cvt_pk_bf16_f32 v61, v99, s0
	s_waitcnt lgkmcnt(0)
	v_pk_mul_f32 v[98:99], v[18:19], v[98:99]
	ds_write_b16 v97, v61 offset:55296
	v_pk_mul_f32 v[18:19], v[54:55], v[102:103]
	v_mov_b32_e32 v100, v51
	v_cvt_pk_bf16_f32 v54, v18, s0
	ds_write_b16 v48, v54 offset:55296
	v_pk_mov_b32 v[54:55], v[104:105], v[50:51] op_sel:[1,0]
	v_add_u32_e32 v111, s34, v114
	v_pk_mul_f32 v[54:55], v[34:35], v[54:55] op_sel_hi:[0,1]
	v_pk_fma_f32 v[54:55], v[32:33], v[104:105], v[54:55] op_sel_hi:[0,1,1]
	v_pk_fma_f32 v[54:55], v[36:37], v[50:51], v[54:55] op_sel_hi:[0,1,1]
	v_pk_add_f32 v[54:55], v[38:39], v[54:55] op_sel_hi:[0,1]
	v_mul_f32_e32 v48, 0xbfb8aa3b, v54
	v_exp_f32_e32 v48, v48
	v_mul_f32_e32 v61, 0xbfb8aa3b, v55
	v_exp_f32_e32 v61, v61
	v_cvt_pk_bf16_f32 v104, v19, s0
	ds_write_b16 v52, v104 offset:55296
	v_mov_b32_e32 v52, v101
	v_pk_mul_f32 v[100:101], v[34:35], v[100:101] op_sel_hi:[0,1]
	v_add_f32_e32 v48, 1.0, v48
	v_pk_fma_f32 v[50:51], v[32:33], v[50:51], v[100:101] op_sel_hi:[0,1,1]
	v_rcp_f32_e32 v102, v48
	v_add_f32_e32 v48, 1.0, v61
	v_pk_fma_f32 v[50:51], v[36:37], v[52:53], v[50:51] op_sel_hi:[0,1,1]
	v_rcp_f32_e32 v103, v48
	v_pk_add_f32 v[50:51], v[38:39], v[50:51] op_sel_hi:[0,1]
	v_mul_f32_e32 v52, 0xbfb8aa3b, v50
	v_exp_f32_e32 v52, v52
	v_mul_f32_e32 v53, 0xbfb8aa3b, v51
	v_exp_f32_e32 v53, v53
	v_pk_mul_f32 v[54:55], v[54:55], v[102:103]
	v_pk_mul_f32 v[104:105], v[20:21], v[18:19]
	v_cvt_pk_bf16_f32 v48, v54, s0
	ds_write_b16 v110, v48 offset:55296
	v_add_f32_e32 v48, 1.0, v52
	ds_read_b128 v[18:21], v111
	v_rcp_f32_e32 v52, v48
	v_add_f32_e32 v48, 1.0, v53
	v_rcp_f32_e32 v53, v48
	v_cvt_pk_bf16_f32 v48, v55, s0
	s_waitcnt lgkmcnt(0)
	v_pk_mul_f32 v[54:55], v[18:19], v[54:55]
	ds_write_b16 v107, v48 offset:55296
	v_pk_mul_f32 v[18:19], v[50:51], v[52:53]
	v_add_u32_e32 v89, 0x190, v86
	v_cvt_pk_bf16_f32 v48, v18, s0
	v_pk_mul_f32 v[50:51], v[20:21], v[18:19]
	ds_write_b16 v108, v48 offset:55296
	v_cvt_pk_bf16_f32 v48, v19, s0
	v_cvt_pk_bf16_f32 v18, v98, v99
	v_cvt_pk_bf16_f32 v19, v104, v105
	v_cvt_pk_bf16_f32 v20, v54, v55
	v_cvt_pk_bf16_f32 v21, v50, v51
	ds_write_b16 v109, v48 offset:55296
	ds_write_b128 v49, v[18:21] offset:18432
	v_ashrrev_i32_e32 v18, 3, v17
	v_and_b32_e32 v18, -16, v18
	v_or_b32_e32 v98, v18, v58
	v_mul_lo_u32 v19, v98, s35
	v_add_u32_e32 v20, 0, v19
	v_lshlrev_b32_e32 v19, 2, v62
	v_add_u32_e32 v101, s34, v19
	s_add_i32 s34, 0, 0x16320
	v_and_b32_e32 v17, 48, v17
	v_add_u32_e32 v102, s34, v19
	v_add_u32_e32 v103, s9, v19
	v_mov_b32_e32 v19, 0x6590
	v_add_u32_e32 v99, v20, v17
	v_add_u32_e32 v100, 0, v17
	v_lshlrev_b32_e32 v17, 2, v116
	v_cndmask_b32_e64 v105, v19, 0, s[46:47]
	v_lshlrev_b32_e32 v19, 3, v116
	v_lshlrev_b32_e32 v18, 1, v18
	v_add3_u32 v106, 0, v19, v18
	v_or_b32_e32 v18, v115, v58
	v_or_b32_e32 v48, v115, v17
	v_mul_u32_u24_e32 v107, 0x90, v18
	v_or_b32_e32 v18, 3, v48
	v_or_b32_e32 v19, 2, v48
	v_cmp_gt_i32_e64 s[62:63], v18, v98
	v_or_b32_e32 v18, 16, v115
	v_cmp_gt_i32_e64 s[64:65], v19, v98
	v_or_b32_e32 v19, v18, v58
	v_or_b32_e32 v17, v18, v17
	v_mul_u32_u24_e32 v108, 0x90, v19
	v_or_b32_e32 v18, 3, v17
	v_or_b32_e32 v19, 2, v17
	v_cmp_gt_i32_e64 s[70:71], v18, v98
	v_cmp_gt_i32_e64 s[72:73], v19, v98
	v_lshl_add_u64 v[18:19], s[12:13], 0, v[168:169]
	v_lshl_add_u64 v[50:51], v[18:19], 0, v[22:23]
	v_lshl_add_u64 v[18:19], s[12:13], 0, v[24:25]
	v_lshl_add_u64 v[52:53], v[18:19], 0, v[26:27]
	v_lshl_add_u64 v[18:19], s[12:13], 0, v[28:29]
	v_lshl_add_u64 v[54:55], v[18:19], 0, v[30:31]
	v_cndmask_b32_e64 v18, v118, v119, s[74:75]
	s_add_u32 s9, s14, s84
	v_or_b32_e32 v18, s76, v18
	v_mov_b32_e32 v19, s77
	s_addc_u32 s34, s15, 0
	v_cndmask_b32_e32 v18, v18, v19, vcc
	s_add_u32 s76, s9, s8
	v_lshlrev_b32_e32 v168, 1, v18
	s_addc_u32 s77, s34, 0
	s_lshl_b32 s8, s31, 1
	v_lshlrev_b32_e32 v21, 1, v48
	v_cmp_gt_i32_e64 s[66:67], v17, v98
	v_cmp_lt_i32_e64 s[68:69], v17, v98
	v_lshlrev_b32_e32 v17, 1, v17
	v_lshl_add_u64 v[18:19], s[12:13], 0, v[168:169]
	s_add_u32 s8, s16, s8
	v_add_u32_e32 v90, 0x320, v86
	v_add_u32_e32 v91, 0x4b0, v86
	v_add_u32_e32 v92, 0x640, v86
	v_add_u32_e32 v93, 0x7d0, v86
	v_add_u32_e32 v94, 0x960, v86
	v_cndmask_b32_e64 v104, 64, -1, s[46:47]
	v_cmp_eq_u32_e64 s[46:47], 0, v58
	v_cmp_lt_u32_e64 s[48:49], 1, v58
	v_cmp_lt_u32_e64 s[50:51], 3, v58
	v_cmp_lt_u32_e64 s[52:53], 7, v58
	v_cmp_eq_u32_e64 s[54:55], 0, v60
	v_cmp_lt_u32_e64 s[56:57], 31, v62
	v_cmp_gt_i32_e64 s[58:59], v48, v98
	v_cmp_lt_i32_e64 s[60:61], v48, v98
	v_lshl_add_u64 v[56:57], v[18:19], 0, v[56:57]
	v_mov_b32_e32 v47, v46
	v_mov_b32_e32 v58, v43
	v_mov_b32_e32 v59, v42
	s_addc_u32 s9, s17, 0
	v_lshlrev_b32_e32 v168, 1, v48
	v_add_u32_e32 v109, v20, v21
	v_add_u32_e32 v110, v20, v17
	s_mov_b32 s35, 0
	v_mov_b32_e32 v17, v16
	v_mov_b32_e32 v18, v16
	v_mov_b32_e32 v19, v16
	v_mov_b32_e32 v20, v16
	v_mov_b32_e32 v21, v16
	v_mov_b32_e32 v22, v16
	v_mov_b32_e32 v23, v16
	s_waitcnt lgkmcnt(0)
	s_barrier
	v_lshrrev_b32_e32 v196, 6, v171
	v_lshlrev_b32_e32 v196, 1, v196
	v_bfe_u32 v197, v171, 3, 1
	v_add_u32_e32 v196, v196, v197
	v_lshlrev_b32_e32 v196, 2, v196
	v_bfe_u32 v197, v171, 4, 2
	v_lshlrev_b32_e32 v197, 3, v197
	v_and_b32_e32 v202, 7, v171
	v_add_u32_e32 v197, v197, v202
	v_mul_u32_u24_e32 v198, 0x190, v196
	v_lshl_add_u32 v198, v197, 2, v198
	v_add_u32_e32 v198, 0xfc00, v198
	v_mul_u32_u24_e32 v199, 0x90, v196
	v_lshl_add_u32 v199, v197, 2, v199
	v_mul_u32_u24_e32 v200, 0x120, v197
	v_lshl_add_u32 v200, v196, 1, v200
	v_lshlrev_b32_e32 v201, 2, v196
	v_add_u32_e32 v201, 0x16520, v201
	v_lshlrev_b32_e32 v202, 3, v197
	v_add_u32_e32 v203, 4, v202
	ds_bpermute_b32 v172, v202, v32
	ds_bpermute_b32 v173, v203, v32
	ds_bpermute_b32 v174, v202, v34
	ds_bpermute_b32 v175, v203, v34
	ds_bpermute_b32 v176, v202, v36
	ds_bpermute_b32 v177, v203, v36
	ds_bpermute_b32 v178, v202, v38
	ds_bpermute_b32 v179, v203, v38
	ds_bpermute_b32 v180, v202, v40
	ds_bpermute_b32 v181, v203, v40
	ds_bpermute_b32 v182, v202, v43
	ds_bpermute_b32 v183, v203, v43
	ds_bpermute_b32 v184, v202, v42
	ds_bpermute_b32 v185, v203, v42
	ds_bpermute_b32 v186, v202, v44
	ds_bpermute_b32 v187, v203, v44
	ds_bpermute_b32 v188, v202, v63
	ds_bpermute_b32 v189, v203, v63
	ds_bpermute_b32 v190, v202, v64
	ds_bpermute_b32 v191, v203, v64
	ds_bpermute_b32 v192, v202, v65
	ds_bpermute_b32 v193, v203, v65
	ds_bpermute_b32 v194, v202, v66
	ds_bpermute_b32 v195, v203, v66
	s_waitcnt lgkmcnt(0)
	s_branch .LBB0_443

.LBB0_482:
	s_or_b64 exec, exec, s[8:9]
	s_ashr_i32 s29, s27, 3
	s_cmp_eq_u32 s28, 0
	v_ashrrev_i32_e32 v55, 3, v28
	s_cselect_b64 vcc, -1, 0
	v_sub_u32_e32 v0, 0xff, v55
	s_lshl_b32 s28, s29, 8
	v_cndmask_b32_e32 v0, v0, v55, vcc
	s_add_i32 s28, s28, 0x8000
	v_add_u32_e32 v2, s28, v0
	v_mov_b64_e32 v[0:1], s[12:13]
	v_and_b32_e32 v4, 7, v28
	v_mad_i64_i32 v[0:1], s[8:9], v2, s20, v[0:1]
	s_lshl_b32 s84, s17, 1
	v_lshl_add_u64 v[0:1], v[0:1], 0, s[84:85]
	v_lshlrev_b32_e32 v168, 4, v4
	v_lshrrev_b32_e32 v29, 2, v28
	s_movk_i32 s8, 0xff
	v_lshl_add_u64 v[14:15], v[0:1], 0, v[168:169]
	v_bfe_u32 v56, v28, 2, 6
	v_bitop3_b32 v0, v29, s8, 63 bitop3:0x6c
	v_cndmask_b32_e32 v0, v0, v56, vcc
	v_or_b32_e32 v2, s28, v0
	v_mov_b64_e32 v[0:1], s[14:15]
	v_mad_i64_i32 v[0:1], s[8:9], v2, s21, v[0:1]
	s_lshl_b32 s8, s16, 2
	s_mov_b32 s9, s85
	v_and_b32_e32 v2, 12, v5
	s_waitcnt lgkmcnt(0)
	s_barrier
	global_load_dwordx4 v[6:9], v[14:15], off
	global_load_dwordx4 v[10:13], v[14:15], off offset:512
	v_lshl_add_u64 v[0:1], v[0:1], 0, s[8:9]
	v_lshlrev_b32_e32 v16, 2, v2
	v_mov_b32_e32 v17, v169
	v_lshl_add_u64 v[0:1], v[0:1], 0, v[16:17]
	global_load_dwordx4 v[0:3], v[0:1], off
	s_nop 0
	global_load_dwordx4 v[20:23], v[14:15], off offset:1024
	s_movk_i32 s16, 0x90
	v_mul_lo_u32 v14, v55, s16
	s_waitcnt vmcnt(0)
	v_add3_u32 v57, 0, v14, v168
	v_and_b32_e32 v5, 0x3ffffff0, v5
	v_cmp_gt_i32_e64 s[40:41], s23, v28
	v_lshlrev_b32_e32 v30, 2, v5
	s_waitcnt vmcnt(3)
	ds_write_b128 v57, v[6:9]
	s_waitcnt vmcnt(2)
	ds_write_b128 v57, v[10:13] offset:9216
	v_lshlrev_b32_e32 v6, 1, v55
	v_mul_u32_u24_e32 v7, 0x480, v4
	v_add3_u32 v58, 0, v7, v6
	s_waitcnt vmcnt(0)
	ds_write_b16 v58, v20 offset:18432
	ds_write_b16_d16_hi v58, v20 offset:18576
	ds_write_b16 v58, v21 offset:18720
	ds_write_b16_d16_hi v58, v21 offset:18864
	ds_write_b16 v58, v22 offset:19008
	ds_write_b16_d16_hi v58, v22 offset:19152
	ds_write_b16 v58, v23 offset:19296
	ds_write_b16_d16_hi v58, v23 offset:19440
	s_and_saveexec_b64 s[16:17], s[40:41]
	s_add_i32 s30, 0, 0x12000
	v_add3_u32 v5, s30, v30, v16
	ds_write_b128 v5, v[0:3]
	s_or_b64 exec, exec, s[16:17]
	v_or_b32_e32 v12, 64, v56
	v_xor_b32_e32 v13, 0xbf, v56
	v_add_u32_e32 v0, 64, v55
	v_sub_u32_e32 v1, 0xbf, v55
	v_cndmask_b32_e32 v12, v13, v12, vcc
	v_cndmask_b32_e32 v0, v1, v0, vcc
	v_or_b32_e32 v14, s28, v12
	v_mov_b64_e32 v[12:13], s[14:15]
	v_add_u32_e32 v3, s28, v0
	v_mov_b64_e32 v[0:1], s[12:13]
	v_mad_i64_i32 v[12:13], s[16:17], v14, s21, v[12:13]
	v_lshlrev_b32_e32 v2, 3, v4
	v_ashrrev_i32_e32 v31, 6, v28
	v_mad_i64_i32 v[0:1], s[16:17], v3, s20, v[0:1]
	v_lshl_add_u64 v[12:13], v[12:13], 0, s[8:9]
	v_lshl_add_u64 v[0:1], v[0:1], 0, s[84:85]
	v_lshlrev_b32_e32 v168, 1, v2
	v_lshl_add_u64 v[12:13], v[12:13], 0, v[16:17]
	v_lshl_add_u32 v17, v31, 9, 0
	v_lshl_add_u64 v[8:9], v[0:1], 0, v[168:169]
	v_add_u32_e32 v59, 0x12000, v17
	global_load_dwordx4 v[0:3], v[8:9], off
	global_load_dwordx4 v[4:7], v[8:9], off offset:512
	s_nop 0
	global_load_dwordx4 v[8:11], v[8:9], off offset:1024
	v_readlane_b32 s9, v253, 46
	global_load_dwordx4 v[12:15], v[12:13], off
	s_waitcnt lgkmcnt(0)
	s_barrier
	ds_read_b128 v[20:23], v59
	ds_read_b128 v[24:27], v59 offset:16
	ds_read_b128 v[48:51], v59 offset:32
	ds_read_b128 v[60:63], v59 offset:48
	v_cmp_lt_i32_e64 s[42:43], 0, v31
	s_waitcnt lgkmcnt(3)
	v_mov_b32_e32 v52, v20
	s_waitcnt lgkmcnt(2)
	v_mov_b32_e32 v53, v24
	v_mov_b32_e32 v24, v21
	v_pk_mul_f32 v[20:21], v[34:35], v[24:25]
	v_mov_b32_e32 v24, v22
	v_pk_fma_f32 v[20:21], v[32:33], v[52:53], v[20:21]
	v_mov_b32_e32 v25, v26
	v_pk_fma_f32 v[20:21], v[36:37], v[24:25], v[20:21]
	v_mov_b32_e32 v26, v23
	v_pk_fma_f32 v[20:21], v[38:39], v[26:27], v[20:21]
	v_cmp_lt_i32_e64 s[44:45], 1, v31
	v_add_f32_e32 v17, v54, v20
	v_add_f32_e32 v17, v17, v21
	s_waitcnt lgkmcnt(0)
	v_mov_b32_e32 v21, v60
	v_mov_b32_e32 v60, v49
	v_mov_b32_e32 v20, v48
	v_pk_mul_f32 v[22:23], v[42:43], v[60:61]
	v_cmp_lt_i32_e64 s[46:47], 2, v31
	v_pk_fma_f32 v[20:21], v[40:41], v[20:21], v[22:23]
	v_mov_b32_e32 v22, v50
	v_mov_b32_e32 v23, v62
	v_pk_fma_f32 v[20:21], v[44:45], v[22:23], v[20:21]
	v_mov_b32_e32 v62, v51
	v_pk_fma_f32 v[20:21], v[46:47], v[62:63], v[20:21]
	v_cmp_lt_i32_e64 s[48:49], 3, v31
	v_add_f32_e32 v17, v17, v20
	v_add_f32_e32 v17, v17, v21
	v_min_f32_e32 v18, 0, v17
	v_mul_f32_e64 v17, |v17|, s19
	v_exp_f32_e32 v17, v17
	ds_read_b128 v[20:23], v59 offset:64
	ds_read_b128 v[24:27], v59 offset:80
	v_cmp_lt_i32_e64 s[50:51], 4, v31
	v_cmp_lt_i32_e64 s[52:53], 5, v31
	v_add_f32_e32 v17, 1.0, v17
	v_log_f32_e32 v17, v17
	s_waitcnt lgkmcnt(0)
	v_mov_b32_e32 v49, v24
	v_mov_b32_e32 v24, v21
	v_mov_b32_e32 v48, v20
	v_pk_mul_f32 v[20:21], v[34:35], v[24:25]
	v_mov_b32_e32 v24, v22
	v_pk_fma_f32 v[20:21], v[32:33], v[48:49], v[20:21]
	v_mov_b32_e32 v25, v26
	v_pk_fma_f32 v[20:21], v[36:37], v[24:25], v[20:21]
	v_mov_b32_e32 v26, v23
	v_fmac_f32_e32 v18, 0xbf317218, v17
	v_pk_fma_f32 v[20:21], v[38:39], v[26:27], v[20:21]
	v_fma_f32 v17, v18, s26, 0
	v_add_f32_e32 v18, v54, v20
	v_add_f32_e32 v18, v18, v21
	ds_read_b128 v[20:23], v59 offset:96
	ds_read_b128 v[24:27], v59 offset:112
	v_cmp_lt_i32_e64 s[54:55], 6, v31
	v_cmp_lt_i32_e64 s[56:57], 7, v31
	v_cmp_gt_u32_e64 s[58:59], 64, v28
	s_waitcnt lgkmcnt(1)
	v_mov_b32_e32 v48, v20
	s_waitcnt lgkmcnt(0)
	v_mov_b32_e32 v49, v24
	v_mov_b32_e32 v24, v21
	v_pk_mul_f32 v[20:21], v[42:43], v[24:25]
	v_mov_b32_e32 v24, v22
	v_pk_fma_f32 v[20:21], v[40:41], v[48:49], v[20:21]
	v_mov_b32_e32 v25, v26
	v_pk_fma_f32 v[20:21], v[44:45], v[24:25], v[20:21]
	v_mov_b32_e32 v26, v23
	v_pk_fma_f32 v[20:21], v[46:47], v[26:27], v[20:21]
	ds_read_b128 v[22:25], v59 offset:128
	ds_read_b128 v[48:51], v59 offset:144
	v_add_f32_e32 v18, v18, v20
	v_add_f32_e32 v18, v18, v21
	v_min_f32_e32 v20, 0, v18
	v_mul_f32_e64 v18, |v18|, s19
	v_exp_f32_e32 v18, v18
	s_waitcnt lgkmcnt(0)
	v_mov_b32_e32 v27, v48
	v_mov_b32_e32 v48, v23
	v_mov_b32_e32 v26, v22
	v_add_f32_e32 v18, 1.0, v18
	v_log_f32_e32 v18, v18
	v_pk_mul_f32 v[22:23], v[34:35], v[48:49]
	v_fmac_f32_e32 v20, 0xbf317218, v18
	v_pk_fma_f32 v[22:23], v[32:33], v[26:27], v[22:23]
	v_mov_b32_e32 v26, v24
	v_mov_b32_e32 v27, v50
	v_pk_fma_f32 v[22:23], v[36:37], v[26:27], v[22:23]
	v_mov_b32_e32 v50, v25
	v_pk_fma_f32 v[22:23], v[38:39], v[50:51], v[22:23]
	v_fmamk_f32 v20, v20, 0x3d800000, v17
	v_add_f32_e32 v18, v54, v22
	v_add_f32_e32 v18, v18, v23
	ds_read_b128 v[22:25], v59 offset:160
	ds_read_b128 v[48:51], v59 offset:176
	s_waitcnt lgkmcnt(1)
	v_mov_b32_e32 v26, v22
	s_waitcnt lgkmcnt(0)
	v_mov_b32_e32 v27, v48
	v_mov_b32_e32 v48, v23
	v_pk_mul_f32 v[22:23], v[42:43], v[48:49]
	s_nop 0
	v_pk_fma_f32 v[22:23], v[40:41], v[26:27], v[22:23]
	v_mov_b32_e32 v26, v24
	v_mov_b32_e32 v27, v50
	v_pk_fma_f32 v[22:23], v[44:45], v[26:27], v[22:23]
	v_mov_b32_e32 v50, v25
	v_pk_fma_f32 v[22:23], v[46:47], v[50:51], v[22:23]
	ds_read_b128 v[24:27], v59 offset:192
	ds_read_b128 v[48:51], v59 offset:208
	v_add_f32_e32 v18, v18, v22
	v_add_f32_e32 v18, v18, v23
	v_min_f32_e32 v21, 0, v18
	v_mul_f32_e64 v18, |v18|, s19
	v_exp_f32_e32 v18, v18
	s_waitcnt lgkmcnt(0)
	v_mov_b32_e32 v53, v48
	v_mov_b32_e32 v48, v25
	v_mov_b32_e32 v52, v24
	v_add_f32_e32 v18, 1.0, v18
	v_log_f32_e32 v18, v18
	v_pk_mul_f32 v[24:25], v[34:35], v[48:49]
	v_mov_b32_e32 v48, v26
	v_pk_fma_f32 v[24:25], v[32:33], v[52:53], v[24:25]
	v_mov_b32_e32 v49, v50
	v_pk_fma_f32 v[24:25], v[36:37], v[48:49], v[24:25]
	v_mov_b32_e32 v50, v27
	v_pk_fma_f32 v[24:25], v[38:39], v[50:51], v[24:25]
	v_fmac_f32_e32 v21, 0xbf317218, v18
	v_add_f32_e32 v18, v54, v24
	v_add_f32_e32 v18, v18, v25
	ds_read_b128 v[24:27], v59 offset:224
	ds_read_b128 v[48:51], v59 offset:240
	v_fmamk_f32 v22, v21, 0x3d800000, v20
	s_waitcnt lgkmcnt(1)
	v_mov_b32_e32 v52, v24
	s_waitcnt lgkmcnt(0)
	v_mov_b32_e32 v53, v48
	v_mov_b32_e32 v48, v25
	v_pk_mul_f32 v[24:25], v[42:43], v[48:49]
	v_mov_b32_e32 v48, v26
	v_pk_fma_f32 v[24:25], v[40:41], v[52:53], v[24:25]
	v_mov_b32_e32 v49, v50
	v_pk_fma_f32 v[24:25], v[44:45], v[48:49], v[24:25]
	v_mov_b32_e32 v50, v27
	v_pk_fma_f32 v[24:25], v[46:47], v[50:51], v[24:25]
	s_nop 0
	v_add_f32_e32 v18, v18, v24
	v_add_f32_e32 v18, v18, v25
	v_min_f32_e32 v21, 0, v18
	v_mul_f32_e64 v18, |v18|, s19
	ds_read_b128 v[24:27], v59 offset:256
	ds_read_b128 v[48:51], v59 offset:272
	v_exp_f32_e32 v18, v18
	s_waitcnt lgkmcnt(1)
	v_mov_b32_e32 v52, v24
	v_add_f32_e32 v18, 1.0, v18
	s_waitcnt lgkmcnt(0)
	v_mov_b32_e32 v53, v48
	v_mov_b32_e32 v48, v25
	v_log_f32_e32 v18, v18
	v_pk_mul_f32 v[24:25], v[34:35], v[48:49]
	v_mov_b32_e32 v48, v26
	v_pk_fma_f32 v[24:25], v[32:33], v[52:53], v[24:25]
	v_mov_b32_e32 v49, v50
	v_pk_fma_f32 v[24:25], v[36:37], v[48:49], v[24:25]
	v_mov_b32_e32 v50, v27
	v_pk_fma_f32 v[24:25], v[38:39], v[50:51], v[24:25]
	v_fmac_f32_e32 v21, 0xbf317218, v18
	v_add_f32_e32 v18, v54, v24
	v_add_f32_e32 v18, v18, v25
	ds_read_b128 v[24:27], v59 offset:288
	ds_read_b128 v[48:51], v59 offset:304
	v_fmamk_f32 v23, v21, 0x3d800000, v22
	s_waitcnt lgkmcnt(1)
	v_mov_b32_e32 v52, v24
	s_waitcnt lgkmcnt(0)
	v_mov_b32_e32 v53, v48
	v_mov_b32_e32 v48, v25
	v_pk_mul_f32 v[24:25], v[42:43], v[48:49]
	v_mov_b32_e32 v48, v26
	v_pk_fma_f32 v[24:25], v[40:41], v[52:53], v[24:25]
	v_mov_b32_e32 v49, v50
	v_pk_fma_f32 v[24:25], v[44:45], v[48:49], v[24:25]
	v_mov_b32_e32 v50, v27
	v_pk_fma_f32 v[24:25], v[46:47], v[50:51], v[24:25]
	ds_read_b128 v[48:51], v59 offset:320
	ds_read_b128 v[60:63], v59 offset:336
	v_add_f32_e32 v18, v18, v24
	v_add_f32_e32 v18, v18, v25
	v_min_f32_e32 v21, 0, v18
	v_mul_f32_e64 v18, |v18|, s19
	v_exp_f32_e32 v18, v18
	s_waitcnt lgkmcnt(0)
	v_mov_b32_e32 v27, v60
	v_mov_b32_e32 v60, v49
	v_mov_b32_e32 v26, v48
	v_pk_mul_f32 v[48:49], v[34:35], v[60:61]
	v_add_f32_e32 v18, 1.0, v18
	v_pk_fma_f32 v[26:27], v[32:33], v[26:27], v[48:49]
	v_mov_b32_e32 v48, v50
	v_mov_b32_e32 v49, v62
	v_pk_fma_f32 v[26:27], v[36:37], v[48:49], v[26:27]
	v_mov_b32_e32 v62, v51
	v_log_f32_e32 v18, v18
	v_pk_fma_f32 v[26:27], v[38:39], v[62:63], v[26:27]
	ds_read_b128 v[48:51], v59 offset:352
	ds_read_b128 v[60:63], v59 offset:368
	v_fmac_f32_e32 v21, 0xbf317218, v18
	v_add_f32_e32 v18, v54, v26
	v_add_f32_e32 v18, v18, v27
	s_waitcnt lgkmcnt(0)
	v_mov_b32_e32 v27, v60
	v_mov_b32_e32 v60, v49
	v_mov_b32_e32 v26, v48
	v_pk_mul_f32 v[48:49], v[42:43], v[60:61]
	v_fmamk_f32 v24, v21, 0x3d800000, v23
	v_pk_fma_f32 v[26:27], v[40:41], v[26:27], v[48:49]
	v_mov_b32_e32 v48, v50
	v_mov_b32_e32 v49, v62
	v_pk_fma_f32 v[26:27], v[44:45], v[48:49], v[26:27]
	v_mov_b32_e32 v62, v51
	v_pk_fma_f32 v[26:27], v[46:47], v[62:63], v[26:27]
	ds_read_b128 v[48:51], v59 offset:384
	ds_read_b128 v[60:63], v59 offset:400
	v_add_f32_e32 v18, v18, v26
	v_add_f32_e32 v18, v18, v27
	v_min_f32_e32 v21, 0, v18
	v_mul_f32_e64 v18, |v18|, s19
	v_exp_f32_e32 v18, v18
	s_waitcnt lgkmcnt(0)
	v_mov_b32_e32 v27, v60
	v_mov_b32_e32 v60, v49
	v_mov_b32_e32 v26, v48
	v_pk_mul_f32 v[48:49], v[34:35], v[60:61]
	v_add_f32_e32 v18, 1.0, v18
	v_pk_fma_f32 v[26:27], v[32:33], v[26:27], v[48:49]
	v_mov_b32_e32 v48, v50
	v_mov_b32_e32 v49, v62
	v_pk_fma_f32 v[26:27], v[36:37], v[48:49], v[26:27]
	v_mov_b32_e32 v62, v51
	v_log_f32_e32 v18, v18
	v_pk_fma_f32 v[26:27], v[38:39], v[62:63], v[26:27]
	ds_read_b128 v[48:51], v59 offset:416
	ds_read_b128 v[60:63], v59 offset:432
	v_fmac_f32_e32 v21, 0xbf317218, v18
	v_add_f32_e32 v18, v54, v26
	v_add_f32_e32 v18, v18, v27
	s_waitcnt lgkmcnt(0)
	v_mov_b32_e32 v27, v60
	v_mov_b32_e32 v60, v49
	v_mov_b32_e32 v26, v48
	v_pk_mul_f32 v[48:49], v[42:43], v[60:61]
	v_fmamk_f32 v25, v21, 0x3d800000, v24
	v_pk_fma_f32 v[26:27], v[40:41], v[26:27], v[48:49]
	v_mov_b32_e32 v48, v50
	v_mov_b32_e32 v49, v62
	v_pk_fma_f32 v[26:27], v[44:45], v[48:49], v[26:27]
	v_mov_b32_e32 v62, v51
	v_pk_fma_f32 v[26:27], v[46:47], v[62:63], v[26:27]
	ds_read_b128 v[48:51], v59 offset:448
	ds_read_b128 v[60:63], v59 offset:464
	v_add_f32_e32 v18, v18, v26
	v_add_f32_e32 v18, v18, v27
	v_min_f32_e32 v21, 0, v18
	v_mul_f32_e64 v18, |v18|, s19
	v_exp_f32_e32 v18, v18
	s_waitcnt lgkmcnt(0)
	v_mov_b32_e32 v53, v60
	v_mov_b32_e32 v60, v49
	v_mov_b32_e32 v52, v48
	v_add_f32_e32 v18, 1.0, v18
	v_log_f32_e32 v18, v18
	v_pk_mul_f32 v[48:49], v[34:35], v[60:61]
	v_fmac_f32_e32 v21, 0xbf317218, v18
	v_pk_fma_f32 v[48:49], v[32:33], v[52:53], v[48:49]
	v_mov_b32_e32 v52, v50
	v_mov_b32_e32 v53, v62
	v_pk_fma_f32 v[48:49], v[36:37], v[52:53], v[48:49]
	v_mov_b32_e32 v62, v51
	v_pk_fma_f32 v[48:49], v[38:39], v[62:63], v[48:49]
	v_fmamk_f32 v26, v21, 0x3d800000, v25
	v_add_f32_e32 v18, v54, v48
	v_add_f32_e32 v18, v18, v49
	ds_read_b128 v[48:51], v59 offset:480
	ds_read_b128 v[60:63], v59 offset:496
	s_waitcnt lgkmcnt(1)
	v_mov_b32_e32 v52, v48
	s_waitcnt lgkmcnt(0)
	v_mov_b32_e32 v53, v60
	v_mov_b32_e32 v60, v49
	v_pk_mul_f32 v[48:49], v[42:43], v[60:61]
	v_lshl_add_u32 v60, v28, 2, s9
	v_pk_fma_f32 v[48:49], v[40:41], v[52:53], v[48:49]
	v_mov_b32_e32 v52, v50
	v_mov_b32_e32 v53, v62
	v_pk_fma_f32 v[48:49], v[44:45], v[52:53], v[48:49]
	v_mov_b32_e32 v62, v51
	v_pk_fma_f32 v[48:49], v[46:47], v[62:63], v[48:49]
	v_lshl_add_u32 v61, v19, 2, s9
	v_add_f32_e32 v18, v18, v48
	v_add_f32_e32 v18, v18, v49
	v_min_f32_e32 v21, 0, v18
	v_mul_f32_e64 v18, |v18|, s19
	v_exp_f32_e32 v18, v18
	s_movk_i32 s9, 0x480
	v_add_f32_e32 v18, 1.0, v18
	v_log_f32_e32 v18, v18
	s_nop 0
	v_fmac_f32_e32 v21, 0xbf317218, v18
	v_fmamk_f32 v27, v21, 0x3d800000, v26
	ds_write_b32 v60, v27
	s_waitcnt lgkmcnt(0)
	s_barrier
	ds_read2st64_b32 v[48:49], v61 offset1:1
	s_waitcnt lgkmcnt(0)
	v_add_f32_e32 v18, 0, v48
	v_cndmask_b32_e64 v21, 0, v18, s[42:43]
	v_add_f32_e32 v48, v49, v21
	v_cndmask_b32_e64 v21, v21, v48, s[44:45]
	v_add_f32_e32 v18, v18, v49
	ds_read2st64_b32 v[48:49], v61 offset0:2 offset1:3
	s_waitcnt lgkmcnt(0)
	v_add_f32_e32 v50, v48, v21
	v_cndmask_b32_e64 v21, v21, v50, s[46:47]
	v_add_f32_e32 v18, v18, v48
	v_add_f32_e32 v48, v49, v21
	v_cndmask_b32_e64 v21, v21, v48, s[48:49]
	v_add_f32_e32 v18, v18, v49
	ds_read2st64_b32 v[48:49], v61 offset0:4 offset1:5
	s_waitcnt lgkmcnt(0)
	v_add_f32_e32 v50, v48, v21
	v_cndmask_b32_e64 v21, v21, v50, s[50:51]
	v_add_f32_e32 v18, v18, v48
	v_add_f32_e32 v48, v49, v21
	v_cndmask_b32_e64 v21, v21, v48, s[52:53]
	v_add_f32_e32 v18, v18, v49
	ds_read2st64_b32 v[48:49], v61 offset0:6 offset1:7
	s_waitcnt lgkmcnt(0)
	v_add_f32_e32 v50, v48, v21
	v_cndmask_b32_e64 v21, v21, v50, s[54:55]
	v_add_f32_e32 v18, v18, v48
	v_add_f32_e32 v48, v49, v21
	v_cndmask_b32_e64 v50, v21, v48, s[56:57]
	v_add_f32_e32 v18, v18, v49
	v_lshlrev_b32_e32 v21, 1, v19
	v_mul_lo_u32 v49, v31, s9
	v_add3_u32 v62, 0, v21, v49
	ds_read_u16 v21, v62
	v_add_f32_e32 v17, v17, v50
	v_mul_f32_e32 v48, 0xbfb8aa3b, v17
	v_mul_f32_e32 v17, 0x3fb8aa3b, v17
	v_exp_f32_e32 v17, v17
	s_waitcnt lgkmcnt(0)
	v_lshlrev_b32_e32 v21, 16, v21
	v_mul_f32_e32 v21, 0x3e000000, v21
	v_exp_f32_e32 v48, v48
	v_mul_f32_e32 v17, v21, v17
	v_cvt_pk_bf16_f32 v17, v17, s0
	ds_write_b16 v62, v17 offset:27648
	v_add_f32_e32 v17, v20, v50
	v_mul_f32_e32 v20, 0xbfb8aa3b, v17
	v_exp_f32_e32 v49, v20
	ds_read_u16 v20, v62 offset:144
	v_mul_f32_e32 v17, 0x3fb8aa3b, v17
	v_exp_f32_e32 v17, v17
	v_mul_f32_e32 v18, 0x3fb8aa3b, v18
	v_exp_f32_e32 v18, v18
	s_waitcnt lgkmcnt(0)
	v_lshlrev_b32_e32 v20, 16, v20
	v_mul_f32_e32 v20, 0x3e000000, v20
	v_mul_f32_e32 v17, v20, v17
	v_cvt_pk_bf16_f32 v17, v17, s0
	ds_write_b16 v62, v17 offset:27792
	ds_read_u16 v17, v62 offset:9216
	ds_read_u16 v20, v62 offset:9360
	s_waitcnt lgkmcnt(0)
	v_lshlrev_b32_e32 v21, 16, v20
	v_lshlrev_b32_e32 v20, 16, v17
	v_mul_f32_e32 v17, v48, v20
	v_cvt_pk_bf16_f32 v17, v17, s0
	ds_write_b16 v62, v17 offset:36864
	v_mul_f32_e32 v17, v49, v21
	v_pk_mul_f32 v[48:49], v[18:19], v[48:49] op_sel_hi:[0,1]
	v_cvt_pk_bf16_f32 v17, v17, s0
	v_pk_mul_f32 v[20:21], v[48:49], v[20:21]
	ds_read_u16 v48, v62 offset:288
	ds_read_u16 v49, v62 offset:432
	ds_write_b16 v62, v17 offset:37008
	v_add_f32_e32 v17, v22, v50
	v_mul_f32_e32 v22, 0xbfb8aa3b, v17
	v_mul_f32_e32 v17, 0x3fb8aa3b, v17
	v_exp_f32_e32 v17, v17
	s_waitcnt lgkmcnt(2)
	v_lshlrev_b32_e32 v48, 16, v48
	v_mul_f32_e32 v48, 0x3e000000, v48
	s_waitcnt lgkmcnt(1)
	v_lshlrev_b32_e32 v49, 16, v49
	v_mul_f32_e32 v17, v17, v48
	v_cvt_pk_bf16_f32 v17, v17, s0
	ds_write_b16 v62, v17 offset:27936
	v_add_f32_e32 v17, v23, v50
	v_mul_f32_e32 v23, 0xbfb8aa3b, v17
	v_mul_f32_e32 v17, 0x3fb8aa3b, v17
	v_exp_f32_e32 v17, v17
	v_mul_f32_e32 v49, 0x3e000000, v49
	ds_read_u16 v48, v62 offset:9504
	v_exp_f32_e32 v22, v22
	v_mul_f32_e32 v17, v17, v49
	v_cvt_pk_bf16_f32 v17, v17, s0
	ds_write_b16 v62, v17 offset:28080
	ds_read_u16 v17, v62 offset:9648
	v_exp_f32_e32 v23, v23
	s_waitcnt lgkmcnt(2)
	v_lshlrev_b32_e32 v48, 16, v48
	v_cvt_pk_bf16_f32 v20, v20, v21
	s_waitcnt lgkmcnt(0)
	v_lshlrev_b32_e32 v49, 16, v17
	v_mul_f32_e32 v17, v22, v48
	v_cvt_pk_bf16_f32 v17, v17, s0
	ds_write_b16 v62, v17 offset:37152
	v_mul_f32_e32 v17, v23, v49
	v_pk_mul_f32 v[22:23], v[18:19], v[22:23] op_sel_hi:[0,1]
	v_cvt_pk_bf16_f32 v17, v17, s0
	v_pk_mul_f32 v[22:23], v[22:23], v[48:49]
	ds_read_u16 v48, v62 offset:576
	ds_write_b16 v62, v17 offset:37296
	v_add_f32_e32 v17, v24, v50
	v_mul_f32_e32 v24, 0xbfb8aa3b, v17
	v_mul_f32_e32 v17, 0x3fb8aa3b, v17
	v_exp_f32_e32 v17, v17
	s_waitcnt lgkmcnt(1)
	v_lshlrev_b32_e32 v48, 16, v48
	v_mul_f32_e32 v48, 0x3e000000, v48
	v_exp_f32_e32 v24, v24
	v_mul_f32_e32 v17, v17, v48
	v_cvt_pk_bf16_f32 v17, v17, s0
	ds_read_u16 v48, v62 offset:720
	ds_write_b16 v62, v17 offset:28224
	v_add_f32_e32 v17, v25, v50
	v_mul_f32_e32 v25, 0xbfb8aa3b, v17
	v_mul_f32_e32 v17, 0x3fb8aa3b, v17
	v_exp_f32_e32 v17, v17
	s_waitcnt lgkmcnt(1)
	v_lshlrev_b32_e32 v48, 16, v48
	v_mul_f32_e32 v48, 0x3e000000, v48
	v_exp_f32_e32 v25, v25
	v_mul_f32_e32 v17, v17, v48
	v_cvt_pk_bf16_f32 v17, v17, s0
	ds_write_b16 v62, v17 offset:28368
	ds_read_u16 v17, v62 offset:9792
	ds_read_u16 v48, v62 offset:9936
	v_cvt_pk_bf16_f32 v21, v22, v23
	s_waitcnt lgkmcnt(0)
	v_lshlrev_b32_e32 v49, 16, v48
	v_lshlrev_b32_e32 v48, 16, v17
	v_mul_f32_e32 v17, v24, v48
	v_cvt_pk_bf16_f32 v17, v17, s0
	ds_write_b16 v62, v17 offset:37440
	v_mul_f32_e32 v17, v25, v49
	v_pk_mul_f32 v[24:25], v[18:19], v[24:25] op_sel_hi:[0,1]
	v_cvt_pk_bf16_f32 v17, v17, s0
	v_pk_mul_f32 v[24:25], v[24:25], v[48:49]
	ds_read_u16 v48, v62 offset:864
	ds_write_b16 v62, v17 offset:37584
	v_add_f32_e32 v17, v26, v50
	v_mul_f32_e32 v26, 0xbfb8aa3b, v17
	v_mul_f32_e32 v17, 0x3fb8aa3b, v17
	v_exp_f32_e32 v17, v17
	s_waitcnt lgkmcnt(1)
	v_lshlrev_b32_e32 v48, 16, v48
	v_mul_f32_e32 v48, 0x3e000000, v48
	v_exp_f32_e32 v26, v26
	v_mul_f32_e32 v17, v17, v48
	v_cvt_pk_bf16_f32 v17, v17, s0
	ds_write_b16 v62, v17 offset:28512
	ds_read_u16 v48, v62 offset:10080
	ds_read_u16 v49, v62 offset:1008
	v_add_f32_e32 v17, v27, v50
	v_mul_f32_e32 v27, 0xbfb8aa3b, v17
	v_mul_f32_e32 v17, 0x3fb8aa3b, v17
	v_exp_f32_e32 v17, v17
	s_waitcnt lgkmcnt(0)
	v_lshlrev_b32_e32 v49, 16, v49
	v_mul_f32_e32 v49, 0x3e000000, v49
	v_exp_f32_e32 v27, v27
	v_mul_f32_e32 v17, v17, v49
	v_cvt_pk_bf16_f32 v17, v17, s0
	ds_write_b16 v62, v17 offset:28656
	ds_read_u16 v17, v62 offset:10224
	v_lshlrev_b32_e32 v48, 16, v48
	v_cvt_pk_bf16_f32 v22, v24, v25
	v_lshlrev_b32_e32 v24, 4, v31
	s_waitcnt lgkmcnt(0)
	v_lshlrev_b32_e32 v49, 16, v17
	v_mul_f32_e32 v17, v26, v48
	v_cvt_pk_bf16_f32 v17, v17, s0
	ds_write_b16 v62, v17 offset:37728
	v_mul_f32_e32 v17, v27, v49
	v_cvt_pk_bf16_f32 v17, v17, s0
	v_pk_mul_f32 v[26:27], v[18:19], v[26:27] op_sel_hi:[0,1]
	ds_write_b16 v62, v17 offset:37872
	v_pk_mul_f32 v[26:27], v[26:27], v[48:49]
	v_mul_u32_u24_e32 v17, 0x90, v19
	v_cvt_pk_bf16_f32 v23, v26, v27
	v_add3_u32 v63, 0, v17, v24
	ds_write_b128 v63, v[20:23] offset:46080
	s_and_saveexec_b64 s[16:17], s[58:59]
	v_lshl_add_u32 v17, v19, 2, 0
	v_add_u32_e32 v17, 0x13800, v17
	ds_write_b32 v17, v18
	s_or_b64 exec, exec, s[16:17]
	s_and_b64 s[16:17], vcc, exec
	s_mov_b32 s9, 0xab34000
	s_cselect_b32 s9, s9, 0xed34000
	v_readlane_b32 s30, v254, 53
	v_readlane_b32 s31, v254, 54
	s_add_u32 s17, s30, s9
	s_addc_u32 s34, s31, 0
	v_lshlrev_b32_e32 v17, 5, v31
	v_bfi_b32 v64, -16, v55, v28
	s_movk_i32 s9, 0x90
	s_add_u32 s30, s12, s84
	v_and_b32_e32 v18, 32, v17
	v_mul_lo_u32 v17, v64, s9
	s_addc_u32 s31, s13, 0
	v_add_u32_e32 v22, 0, v17
	v_and_b32_e32 v17, 48, v28
	s_add_u32 s8, s14, s8
	v_add_u32_e32 v65, v22, v17
	v_add_u32_e32 v66, 0, v17
	s_addc_u32 s9, s15, 0
	v_mov_b32_e32 v17, v169
	v_lshl_add_u64 v[50:51], s[8:9], 0, v[16:17]
	s_add_u32 s8, s17, s84
	v_and_b32_e32 v21, -16, v55
	v_and_b32_e32 v23, 12, v29
	v_lshl_add_u64 v[48:49], s[30:31], 0, v[168:169]
	s_addc_u32 s9, s34, 0
	s_add_i32 s30, 0, 0x13800
	v_lshl_add_u32 v67, v19, 2, s30
	v_lshlrev_b32_e32 v19, 2, v21
	v_lshlrev_b32_e32 v24, 2, v23
	v_and_b32_e32 v20, 15, v28
	v_add3_u32 v69, s30, v19, v24
	v_or_b32_e32 v19, v23, v21
	v_lshl_add_u32 v70, v19, 1, 0
	v_or_b32_e32 v19, v18, v20
	v_mul_u32_u24_e32 v71, 0x90, v19
	v_or_b32_e32 v19, v18, v23
	v_or_b32_e32 v21, 2, v19
	v_cmp_gt_i32_e64 s[64:65], v21, v64
	v_or_b32_e32 v21, 3, v19
	v_cmp_gt_i32_e64 s[66:67], v21, v64
	v_or_b32_e32 v21, 16, v18
	v_or_b32_e32 v20, v21, v20
	s_add_i32 s17, 0, 0x12000
	v_lshlrev_b32_e32 v168, 1, v23
	v_mul_u32_u24_e32 v72, 0x90, v20
	v_or_b32_e32 v20, v21, v23
	v_add3_u32 v68, s17, v30, v16
	v_lshl_add_u64 v[16:17], s[8:9], 0, v[168:169]
	v_or_b32_e32 v21, 2, v20
	v_lshlrev_b32_e32 v168, 1, v18
	v_cmp_gt_i32_e64 s[60:61], v19, v64
	v_cmp_lt_i32_e64 s[62:63], v19, v64
	v_lshlrev_b32_e32 v19, 1, v19
	v_cmp_gt_i32_e64 s[68:69], v20, v64
	v_cmp_lt_i32_e64 s[70:71], v20, v64
	v_cmp_gt_i32_e64 s[72:73], v21, v64
	v_or_b32_e32 v21, 3, v20
	v_lshlrev_b32_e32 v20, 1, v20
	v_lshl_add_u64 v[52:53], v[16:17], 0, v[168:169]
	v_mov_b32_e32 v16, 0
	s_mov_b32 s16, 0
	s_lshl_b32 s17, s29, 13
	v_cmp_gt_i32_e64 s[74:75], v21, v64
	v_add_u32_e32 v73, v22, v19
	v_add_u32_e32 v74, v22, v20
	s_mov_b32 s29, 0
	v_mov_b32_e32 v17, v16
	v_mov_b32_e32 v18, v16
	v_mov_b32_e32 v19, v16
	v_mov_b32_e32 v20, v16
	v_mov_b32_e32 v21, v16
	v_mov_b32_e32 v22, v16
	v_mov_b32_e32 v23, v16
	s_waitcnt lgkmcnt(0)
	s_barrier
	v_mov_b32_e32 v204, v32
	v_mov_b32_e32 v205, v34
	v_mov_b32_e32 v206, v36
	v_mov_b32_e32 v207, v38
	v_mov_b32_e32 v208, v33
	v_mov_b32_e32 v209, v35
	v_mov_b32_e32 v210, v37
	v_mov_b32_e32 v211, v39
	v_mov_b32_e32 v212, v40
	v_mov_b32_e32 v213, v42
	v_mov_b32_e32 v214, v44
	v_mov_b32_e32 v215, v46
	v_mov_b32_e32 v216, v41
	v_mov_b32_e32 v217, v43
	v_mov_b32_e32 v218, v45
	v_mov_b32_e32 v219, v47
	v_and_b32_e32 v240, 7, v171
	v_lshrrev_b32_e32 v239, 3, v171
	v_lshlrev_b32_e32 v239, 1, v239
	v_add_u32_e32 v222, 0, v240
	v_and_b32_e32 v222, 7, v222
	v_lshl_add_u32 v222, v240, 3, v222
	v_mul_u32_u24_e32 v222, 0x90, v222
	v_add_u32_e32 v222, v222, v239
	v_add_u32_e32 v223, 1, v240
	v_and_b32_e32 v223, 7, v223
	v_lshl_add_u32 v223, v240, 3, v223
	v_mul_u32_u24_e32 v223, 0x90, v223
	v_add_u32_e32 v223, v223, v239
	v_add_u32_e32 v224, 2, v240
	v_and_b32_e32 v224, 7, v224
	v_lshl_add_u32 v224, v240, 3, v224
	v_mul_u32_u24_e32 v224, 0x90, v224
	v_add_u32_e32 v224, v224, v239
	v_add_u32_e32 v225, 3, v240
	v_and_b32_e32 v225, 7, v225
	v_lshl_add_u32 v225, v240, 3, v225
	v_mul_u32_u24_e32 v225, 0x90, v225
	v_add_u32_e32 v225, v225, v239
	v_add_u32_e32 v226, 4, v240
	v_and_b32_e32 v226, 7, v226
	v_lshl_add_u32 v226, v240, 3, v226
	v_mul_u32_u24_e32 v226, 0x90, v226
	v_add_u32_e32 v226, v226, v239
	v_add_u32_e32 v227, 5, v240
	v_and_b32_e32 v227, 7, v227
	v_lshl_add_u32 v227, v240, 3, v227
	v_mul_u32_u24_e32 v227, 0x90, v227
	v_add_u32_e32 v227, v227, v239
	v_add_u32_e32 v228, 6, v240
	v_and_b32_e32 v228, 7, v228
	v_lshl_add_u32 v228, v240, 3, v228
	v_mul_u32_u24_e32 v228, 0x90, v228
	v_add_u32_e32 v228, v228, v239
	v_add_u32_e32 v229, 7, v240
	v_and_b32_e32 v229, 7, v229
	v_lshl_add_u32 v229, v240, 3, v229
	v_mul_u32_u24_e32 v229, 0x90, v229
	v_add_u32_e32 v229, v229, v239
	v_and_b32_e32 v230, 1, v171
	v_lshlrev_b32_e32 v230, 4, v230
	s_branch .LBB0_488

.LBB0_488:
	ds_read_b128 v[132:135], v65 offset:27648
	v_add_u32_e32 v129, v66, v71
	ds_read_b128 v[136:139], v129 offset:36864
	ds_read_b128 v[140:143], v65 offset:27712
	ds_read_b128 v[144:147], v129 offset:36928
	ds_read_b128 v[148:151], v129 offset:64512
	ds_read_b128 v[152:155], v129 offset:64576
	v_add_u32_e32 v130, v66, v72
	ds_read_b128 v[156:159], v130 offset:36864
	ds_read_b128 v[160:163], v130 offset:64512
	ds_read_b128 v[164:167], v130 offset:64576
	s_and_b32 s35, s29, 1
	s_cmpk_eq_i32 s29, 0x83
	s_waitcnt lgkmcnt(5)
	v_mfma_f32_16x16x32_bf16 v[28:31], v[136:139], v[132:135], 0
	v_mfma_f32_16x16x32_bf16 v[28:31], v[144:147], v[140:143], v[28:31]
	s_nop 7
	v_cndmask_b32_e64 v28, v28, 0, s[60:61]
	v_cndmask_b32_e64 v29, 0, v29, s[62:63]
	v_cndmask_b32_e64 v30, v30, 0, s[64:65]
	v_cndmask_b32_e64 v31, v31, 0, s[66:67]
	v_cvt_pk_bf16_f32 v28, v28, v29
	v_cvt_pk_bf16_f32 v29, v30, v31
	ds_write_b64 v73, v[28:29] offset:55296
	s_waitcnt lgkmcnt(5)
	v_mfma_f32_16x16x32_bf16 v[28:31], v[148:151], v[132:135], 0
	v_add_u32_e32 v75, v66, v72
	ds_read_b128 v[84:87], v75 offset:36928
	s_waitcnt lgkmcnt(0)
	v_mfma_f32_16x16x32_bf16 v[28:31], v[152:155], v[140:143], v[28:31]
	v_mfma_f32_16x16x32_bf16 v[80:83], v[156:159], v[132:135], 0
	v_mfma_f32_16x16x32_bf16 v[80:83], v[84:87], v[140:143], v[80:83]
	s_nop 7
	v_cndmask_b32_e64 v80, v80, 0, s[68:69]
	v_cndmask_b32_e64 v81, 0, v81, s[70:71]
	v_cndmask_b32_e64 v82, v82, 0, s[72:73]
	v_cndmask_b32_e64 v83, v83, 0, s[74:75]
	v_cvt_pk_bf16_f32 v80, v80, v81
	v_cvt_pk_bf16_f32 v81, v82, v83
	ds_write_b64 v74, v[80:81] offset:55296
	v_mfma_f32_16x16x32_bf16 v[24:27], v[160:163], v[132:135], 0
	v_mfma_f32_16x16x32_bf16 v[24:27], v[164:167], v[140:143], v[24:27]
	s_cbranch_scc1 .LBB0_493
	s_xor_b32 s30, s35, 1
	s_mul_i32 s31, s30, 0x13a00
	s_waitcnt vmcnt(0)
	v_add_u32_e32 v75, s31, v57
	s_waitcnt vmcnt(3)
	ds_write_b128 v75, v[0:3]
	s_waitcnt vmcnt(2)
	ds_write_b128 v75, v[4:7] offset:9216
	v_add_u32_e32 v75, s31, v58
	s_mul_i32 s34, s30, 0x8600
	s_waitcnt vmcnt(1)
	v_alignbit_b32 v231, v9, v8, v230
	v_alignbit_b32 v232, v10, v9, v230
	v_alignbit_b32 v233, v11, v10, v230
	v_alignbit_b32 v234, v8, v11, v230
	v_and_b32_e32 v240, 2, v171
	v_cmp_ne_u32_e64 s[8:9], 0, v240
	v_and_b32_e32 v240, 4, v171
	s_nop 0
	v_cndmask_b32_e64 v235, v231, v232, s[8:9]
	v_cndmask_b32_e64 v236, v232, v233, s[8:9]
	v_cndmask_b32_e64 v237, v233, v234, s[8:9]
	v_cndmask_b32_e64 v238, v234, v231, s[8:9]
	v_cmp_ne_u32_e64 s[8:9], 0, v240
	s_nop 1
	v_cndmask_b32_e64 v231, v235, v237, s[8:9]
	v_cndmask_b32_e64 v232, v236, v238, s[8:9]
	v_cndmask_b32_e64 v233, v237, v235, s[8:9]
	v_cndmask_b32_e64 v234, v238, v236, s[8:9]
	v_add_u32_e32 v239, s31, v222
	ds_write_b16 v239, v231 offset:18432
	v_add_u32_e32 v239, s31, v223
	ds_write_b16_d16_hi v239, v231 offset:18432
	v_add_u32_e32 v239, s31, v224
	ds_write_b16 v239, v232 offset:18432
	v_add_u32_e32 v239, s31, v225
	ds_write_b16_d16_hi v239, v232 offset:18432
	v_add_u32_e32 v239, s31, v226
	ds_write_b16 v239, v233 offset:18432
	v_add_u32_e32 v239, s31, v227
	ds_write_b16_d16_hi v239, v233 offset:18432
	v_add_u32_e32 v239, s31, v228
	ds_write_b16 v239, v234 offset:18432
	v_add_u32_e32 v239, s31, v229
	ds_write_b16_d16_hi v239, v234 offset:18432
	s_and_saveexec_b64 s[8:9], s[40:41]
	s_cbranch_execz .LBB0_491
	v_add_u32_e32 v75, s34, v68
	s_waitcnt vmcnt(0)
	ds_write_b128 v75, v[12:15]
